# v14 + per-tile workgroup barrier moved from end of tile step to before V pre-reads (after QK MFMAs) in A and B NOMAX flash loops
# speedup vs baseline: 1.0147x; 1.0147x over previous
; #define SBAR() __builtin_amdgcn_sched_barrier(0)
; __device__ __forceinline__ s16x4 vtr(lds_cptr p) { return __builtin_bit_cast(s16x4, __builtin_amdgcn_ds_read_tr16_b64_v4i16((__attribute__((address_space(3))) v4i16_t*)p)); }
; #define PIN(x) asm volatile("" : "+v"(x))
; __device__ __forceinline__ void add_bias(f32x16& p0, f32x16& p1, const float* tb, int relb, int hi) {
;   const float* t = tb + relb + 4 * hi;
; #pragma unroll
;   for (int r = 0; r < 16; ++r) { p0[r] += t[(r & 3) + 8 * (r >> 2)]; p1[r] += t[32 + (r & 3) + 8 * (r >> 2)]; }
; }
; template <int DK, bool NOMAX> ...
;     ...
;   for (int d0 = 0; d0 < NS; ++d0) {
;     if (d0 == 0) { c0 = __builtin_amdgcn_mfma_f32_32x32x16_bf16(kf[0][0], qr[0], f32x16{}, 0, 0, 0); c1 = __builtin_amdgcn_mfma_f32_32x32x16_bf16(kf[0][1], qr[0], f32x16{}, 0, 0, 0); }
;     else { c0 = __builtin_amdgcn_mfma_f32_32x32x16_bf16(kf[d0 & 1][0], qr[d0], c0, 0, 0, 0); c1 = __builtin_amdgcn_mfma_f32_32x32x16_bf16(kf[d0 & 1][1], qr[d0], c1, 0, 0, 0); }
;     if (d0 + 2 < NS) KRD_(d0 & 1, d0 + 2);
;     if constexpr (NOMAX) { }
;     else {
; #pragma unroll
;     for (int r = d0 * RPS; r < (d0 + 1) * RPS; ++r) { p1[r] = __builtin_amdgcn_exp2f(p1[r]); psa += p0[r]; }
;     if (d0 > 0) {
; #pragma unroll
;       for (int r = (d0 - 1) * RPS; r < d0 * RPS; ++r) psb += p1[r]; } }
;     if constexpr (NOMAX) {
;       if (d0 == NS / 4 - 1) { PK4R(p0, 0, pa[0]); PIN(pa[0]); }
;       if (d0 == NS / 2 - 1) { PK4R(p0, 8, pa[1]); PIN(pa[1]); }
;       if (d0 == 3 * NS / 4 - 1) { PK4R(p1, 0, pa[2]); PIN(pa[2]); }
;       if (d0 == NS - 1) { PK4R(p1, 8, pa[3]); PIN(pa[3]); }
;     } else {
;     if (d0 == NS / 2 - 1) { PK4R(p0, 0, pa[0]); PIN(pa[0]); }
;     if (d0 == NS / 2) { PK4R(p0, 8, pa[1]); PIN(pa[1]); }
;     if (d0 == NS - 1) { PK4R(p1, 0, pa[2]); PIN(pa[2]); }
;     }
;     if (d0 == NS - 1) {
;       vl[0] = vtr(vp + v_rd_off(0, 0, 0)); vh[0] = vtr(vp + v_rd_off(0, 0, 1)); vl[1] = vtr(vp + v_rd_off(1, 0, 0)); vh[1] = vtr(vp + v_rd_off(1, 0, 1)); }
;     PIN(p1); PIN(psa); PIN(psb);
;     SBAR();
;   }
.LBB0_220:
	s_mov_b32 s6, s96
	s_mov_b32 s96, s4
	s_add_i32 s4, s63, 0xffff4000
	s_and_b32 s59, s4, 0xc000
	s_add_i32 s4, s59, 0
	v_add_u32_e32 v213, s96, v187
	s_waitcnt lgkmcnt(0)
	v_mfma_f32_32x32x16_bf16 v[128:143], v[116:119], v[156:159], 0
	v_add_u32_e32 v0, s4, v207
	ds_read_b128 v[2:5], v0
	ds_read_b128 v[164:167], v0 offset:4096
	v_cvt_pk_bf16_f32 v96, v96, v97
	v_cvt_pk_bf16_f32 v97, v98, v99
	v_cvt_pk_bf16_f32 v98, v100, v101
	v_cvt_pk_bf16_f32 v99, v102, v103
	v_mfma_f32_32x32x16_bf16 v[112:127], v[112:115], v[156:159], 0
	v_permlane32_swap_b32_e32 v96, v98
	v_permlane32_swap_b32_e32 v97, v99
	v_mfma_f32_32x32x16_bf16 v[128:143], v[10:13], v[152:155], v[128:143]
	v_mfma_f32_32x32x16_bf16 v[112:127], v[6:9], v[152:155], v[112:127]
	v_add_u32_e32 v6, s4, v208
	ds_read_b128 v[100:103], v6
	ds_read_b128 v[214:217], v6 offset:4096
	v_cvt_pk_bf16_f32 v10, v104, v105
	v_cvt_pk_bf16_f32 v11, v106, v107
	v_cvt_pk_bf16_f32 v12, v108, v109
	v_cvt_pk_bf16_f32 v13, v110, v111
	s_nop 0
	v_permlane32_swap_b32_e32 v10, v12
	v_permlane32_swap_b32_e32 v11, v13
	s_waitcnt lgkmcnt(3)
	v_mfma_f32_32x32x16_bf16 v[128:143], v[2:5], v[148:151], v[128:143]
	v_cvt_pk_bf16_f32 v6, v80, v81
	v_cvt_pk_bf16_f32 v7, v82, v83
	v_cvt_pk_bf16_f32 v8, v84, v85
	v_cvt_pk_bf16_f32 v9, v86, v87
	s_nop 0
	v_permlane32_swap_b32_e32 v6, v8
	s_waitcnt lgkmcnt(2)
	v_mfma_f32_32x32x16_bf16 v[112:127], v[164:167], v[148:151], v[112:127]
	v_permlane32_swap_b32_e32 v7, v9
	s_nop 0
	v_cvt_pk_bf16_f32 v2, v88, v89
	v_cvt_pk_bf16_f32 v3, v90, v91
	v_cvt_pk_bf16_f32 v4, v92, v93
	v_cvt_pk_bf16_f32 v5, v94, v95
	s_waitcnt lgkmcnt(1)
	v_mfma_f32_32x32x16_bf16 v[128:143], v[100:103], v[144:147], v[128:143]
	v_permlane32_swap_b32_e32 v2, v4
	v_permlane32_swap_b32_e32 v3, v5
	s_cmpk_gt_i32 s97, 0x7b
	s_cbranch_scc1 .Lmy_mb0_a1_1
	s_waitcnt vmcnt(3) lgkmcnt(0)
	s_barrier
.Lmy_mbj_a1_1:
	ds_read_b64_tr_b16 v[104:105], v213
	ds_read_b64_tr_b16 v[106:107], v213 offset:2048
	ds_read_b64_tr_b16 v[100:101], v213 offset:512
	ds_read_b64_tr_b16 v[102:103], v213 offset:2560
	s_waitcnt lgkmcnt(4)
	v_mfma_f32_32x32x16_bf16 v[112:127], v[214:217], v[144:147], v[112:127]
	v_add_u32_e32 v216, s7, v205
	v_add_u32_e32 v0, 0xffffffa1, v216
	v_cmp_gt_i32_e32 vcc, s67, v0
	v_mov_b32_e32 v215, v199
	s_and_saveexec_b64 s[4:5], vcc
	s_cbranch_execz .LBB0_224
	v_subrev_u32_e32 v0, 64, v216
	v_cmp_lt_i32_e32 vcc, s77, v0
	v_mov_b32_e32 v215, v198
	s_and_saveexec_b64 s[18:19], vcc
	s_cbranch_execz .LBB0_223
	ds_read2_b32 v[80:81], v211 offset1:1
	ds_read2_b32 v[82:83], v211 offset0:2 offset1:3
	ds_read2_b32 v[84:85], v211 offset0:8 offset1:9
	ds_read2_b32 v[86:87], v211 offset0:10 offset1:11
	ds_read2_b32 v[88:89], v211 offset0:16 offset1:17
	ds_read2_b32 v[90:91], v211 offset0:18 offset1:19
	ds_read2_b32 v[92:93], v211 offset0:24 offset1:25
	ds_read2_b32 v[94:95], v211 offset0:26 offset1:27
	ds_read2_b32 v[108:109], v211 offset0:32 offset1:33
	ds_read2_b32 v[110:111], v211 offset0:34 offset1:35
	ds_read2_b32 v[164:165], v211 offset0:40 offset1:41
	ds_read2_b32 v[166:167], v211 offset0:42 offset1:43
	s_waitcnt lgkmcnt(0)
	v_pk_add_f32 v[128:129], v[128:129], v[80:81]
	v_pk_add_f32 v[140:141], v[140:141], v[92:93]
	v_pk_add_f32 v[138:139], v[138:139], v[90:91]
	v_pk_add_f32 v[136:137], v[136:137], v[88:89]
	ds_read2_b32 v[80:81], v211 offset0:48 offset1:49
	ds_read2_b32 v[88:89], v211 offset0:50 offset1:51
	ds_read2_b32 v[90:91], v211 offset0:56 offset1:57
	ds_read2_b32 v[92:93], v211 offset0:58 offset1:59
	v_pk_add_f32 v[142:143], v[142:143], v[94:95]
	v_pk_add_f32 v[134:135], v[134:135], v[86:87]
	v_pk_add_f32 v[132:133], v[132:133], v[84:85]
	v_pk_add_f32 v[130:131], v[130:131], v[82:83]
	v_pk_add_f32 v[112:113], v[112:113], v[108:109]
	s_waitcnt lgkmcnt(0)
	v_pk_add_f32 v[126:127], v[126:127], v[92:93]
	v_pk_add_f32 v[124:125], v[124:125], v[90:91]
	v_pk_add_f32 v[122:123], v[122:123], v[88:89]
	v_pk_add_f32 v[120:121], v[120:121], v[80:81]
	v_pk_add_f32 v[118:119], v[118:119], v[166:167]
	v_pk_add_f32 v[116:117], v[116:117], v[164:165]
	v_pk_add_f32 v[114:115], v[114:115], v[110:111]
	v_mov_b32_e32 v215, 0

; #define SBAR() __builtin_amdgcn_sched_barrier(0)
; __device__ __forceinline__ s16x4 vtr(lds_cptr p) { return __builtin_bit_cast(s16x4, __builtin_amdgcn_ds_read_tr16_b64_v4i16((__attribute__((address_space(3))) v4i16_t*)p)); }
; #define PIN(x) asm volatile("" : "+v"(x))
; template <int DK, bool NOMAX> ...
;     ...
;   for (int d0 = 0; d0 < NS; ++d0) {
;     if (d0 == 0) { c0 = __builtin_amdgcn_mfma_f32_32x32x16_bf16(kf[0][0], qr[0], f32x16{}, 0, 0, 0); c1 = __builtin_amdgcn_mfma_f32_32x32x16_bf16(kf[0][1], qr[0], f32x16{}, 0, 0, 0); }
;     else { c0 = __builtin_amdgcn_mfma_f32_32x32x16_bf16(kf[d0 & 1][0], qr[d0], c0, 0, 0, 0); c1 = __builtin_amdgcn_mfma_f32_32x32x16_bf16(kf[d0 & 1][1], qr[d0], c1, 0, 0, 0); }
;     if (d0 + 2 < NS) KRD_(d0 & 1, d0 + 2);
;     if constexpr (NOMAX) { }
;     else {
; #pragma unroll
;     for (int r = d0 * RPS; r < (d0 + 1) * RPS; ++r) { p1[r] = __builtin_amdgcn_exp2f(p1[r]); psa += p0[r]; }
;     if (d0 > 0) {
; #pragma unroll
;       for (int r = (d0 - 1) * RPS; r < d0 * RPS; ++r) psb += p1[r]; } }
;     if constexpr (NOMAX) {
;       if (d0 == NS / 4 - 1) { PK4R(p0, 0, pa[0]); PIN(pa[0]); }
;       if (d0 == NS / 2 - 1) { PK4R(p0, 8, pa[1]); PIN(pa[1]); }
;       if (d0 == 3 * NS / 4 - 1) { PK4R(p1, 0, pa[2]); PIN(pa[2]); }
;       if (d0 == NS - 1) { PK4R(p1, 8, pa[3]); PIN(pa[3]); }
;     } else {
;     if (d0 == NS / 2 - 1) { PK4R(p0, 0, pa[0]); PIN(pa[0]); }
;     if (d0 == NS / 2) { PK4R(p0, 8, pa[1]); PIN(pa[1]); }
;     if (d0 == NS - 1) { PK4R(p1, 0, pa[2]); PIN(pa[2]); }
;     }
;     if (d0 == NS - 1) {
;       vl[0] = vtr(vp + v_rd_off(0, 0, 0)); vh[0] = vtr(vp + v_rd_off(0, 0, 1)); vl[1] = vtr(vp + v_rd_off(1, 0, 0)); vh[1] = vtr(vp + v_rd_off(1, 0, 1)); }
;     PIN(p1); PIN(psa); PIN(psb);
;     SBAR();
;   }
.LBB0_230:
	s_mov_b64 s[4:5], -1
	s_waitcnt lgkmcnt(0)
.LBB0_232:
.LBB0_234:
	v_add_u32_e32 v217, s6, v187
	v_mfma_f32_32x32x16_bf16 v[96:111], v[80:83], v[156:159], 0
	v_add_u32_e32 v212, s94, v207
	ds_read_b128 v[2:5], v212
	ds_read_b128 v[218:221], v212 offset:4096
	v_cvt_pk_bf16_f32 v128, v128, v129
	v_cvt_pk_bf16_f32 v129, v130, v131
	v_cvt_pk_bf16_f32 v130, v132, v133
	v_cvt_pk_bf16_f32 v131, v134, v135
	v_mfma_f32_32x32x16_bf16 v[80:95], v[84:87], v[156:159], 0
	v_permlane32_swap_b32_e32 v128, v130
	v_permlane32_swap_b32_e32 v129, v131
	v_mfma_f32_32x32x16_bf16 v[96:111], v[6:9], v[152:155], v[96:111]
	v_add_u32_e32 v6, s94, v208
	ds_read_b128 v[132:135], v6
	ds_read_b128 v[222:225], v6 offset:4096
	v_mfma_f32_32x32x16_bf16 v[80:95], v[10:13], v[152:155], v[80:95]
	v_cvt_pk_bf16_f32 v10, v136, v137
	v_cvt_pk_bf16_f32 v11, v138, v139
	v_cvt_pk_bf16_f32 v12, v140, v141
	v_cvt_pk_bf16_f32 v13, v142, v143
	s_nop 0
	v_permlane32_swap_b32_e32 v10, v12
	v_permlane32_swap_b32_e32 v11, v13
	s_waitcnt lgkmcnt(3)
	v_mfma_f32_32x32x16_bf16 v[96:111], v[2:5], v[148:151], v[96:111]
	v_cvt_pk_bf16_f32 v6, v112, v113
	v_cvt_pk_bf16_f32 v7, v114, v115
	v_cvt_pk_bf16_f32 v8, v116, v117
	v_cvt_pk_bf16_f32 v9, v118, v119
	s_nop 0
	v_permlane32_swap_b32_e32 v6, v8
	s_waitcnt lgkmcnt(2)
	v_mfma_f32_32x32x16_bf16 v[80:95], v[218:221], v[148:151], v[80:95]
	v_permlane32_swap_b32_e32 v7, v9
	s_nop 0
	v_cvt_pk_bf16_f32 v2, v120, v121
	v_cvt_pk_bf16_f32 v3, v122, v123
	v_cvt_pk_bf16_f32 v4, v124, v125
	v_cvt_pk_bf16_f32 v5, v126, v127
	s_waitcnt lgkmcnt(1)
	v_mfma_f32_32x32x16_bf16 v[96:111], v[132:135], v[144:147], v[96:111]
	v_permlane32_swap_b32_e32 v2, v4
	v_permlane32_swap_b32_e32 v3, v5
	s_cmpk_gt_i32 s97, 0x7c
	s_cbranch_scc1 .Lmy_mb0_a1_2
	s_waitcnt vmcnt(3) lgkmcnt(0)
	s_barrier
.Lmy_mbj_a1_2:
	ds_read_b64_tr_b16 v[136:137], v217
	ds_read_b64_tr_b16 v[138:139], v217 offset:2048
	ds_read_b64_tr_b16 v[132:133], v217 offset:512
	ds_read_b64_tr_b16 v[134:135], v217 offset:2560
	s_waitcnt lgkmcnt(4)
	v_mfma_f32_32x32x16_bf16 v[80:95], v[222:225], v[144:147], v[80:95]
	v_subrev_u32_e32 v112, 31, v216
	v_cmp_gt_i32_e32 vcc, s67, v112
	v_mov_b32_e32 v212, v199
	s_and_saveexec_b64 s[4:5], vcc
	s_cbranch_execz .LBB0_238
	v_cmp_ge_i32_e32 vcc, s7, v181
	v_mov_b32_e32 v212, v198
	s_and_saveexec_b64 s[94:95], vcc
	s_cbranch_execz .LBB0_237
	ds_read2_b32 v[112:113], v211 offset0:64 offset1:65
	ds_read2_b32 v[114:115], v211 offset0:66 offset1:67
	ds_read2_b32 v[116:117], v211 offset0:72 offset1:73
	ds_read2_b32 v[118:119], v211 offset0:74 offset1:75
	ds_read2_b32 v[120:121], v211 offset0:80 offset1:81
	ds_read2_b32 v[122:123], v211 offset0:82 offset1:83
	ds_read2_b32 v[124:125], v211 offset0:88 offset1:89
	ds_read2_b32 v[126:127], v211 offset0:90 offset1:91
	ds_read2_b32 v[140:141], v211 offset0:96 offset1:97
	ds_read2_b32 v[142:143], v211 offset0:98 offset1:99
	ds_read2_b32 v[218:219], v211 offset0:104 offset1:105
	ds_read2_b32 v[220:221], v211 offset0:106 offset1:107
	s_waitcnt lgkmcnt(0)
	v_pk_add_f32 v[96:97], v[96:97], v[112:113]
	v_pk_add_f32 v[108:109], v[108:109], v[124:125]
	v_pk_add_f32 v[106:107], v[106:107], v[122:123]
	v_pk_add_f32 v[104:105], v[104:105], v[120:121]
	ds_read2_b32 v[112:113], v211 offset0:112 offset1:113
	ds_read2_b32 v[120:121], v211 offset0:114 offset1:115
	ds_read2_b32 v[122:123], v211 offset0:120 offset1:121
	ds_read2_b32 v[124:125], v211 offset0:122 offset1:123
	v_pk_add_f32 v[110:111], v[110:111], v[126:127]
	v_pk_add_f32 v[102:103], v[102:103], v[118:119]
	v_pk_add_f32 v[100:101], v[100:101], v[116:117]
	v_pk_add_f32 v[98:99], v[98:99], v[114:115]
	v_pk_add_f32 v[80:81], v[80:81], v[140:141]
	s_waitcnt lgkmcnt(0)
	v_pk_add_f32 v[94:95], v[94:95], v[124:125]
	v_pk_add_f32 v[92:93], v[92:93], v[122:123]
	v_pk_add_f32 v[90:91], v[90:91], v[120:121]
	v_pk_add_f32 v[88:89], v[88:89], v[112:113]
	v_pk_add_f32 v[86:87], v[86:87], v[220:221]
	v_pk_add_f32 v[84:85], v[84:85], v[218:219]
	v_pk_add_f32 v[82:83], v[82:83], v[142:143]
	v_mov_b32_e32 v212, 0

; template <int DK, int LDK, bool BIAS, bool NOMAX> ...
;     ...
;   for (int j = 1; j + 1 < NT; j += 2) {
;     STEPT(pB0, pB1, pA0, pA1, alA, alB, j);
;     STEPT(pA0, pA1, pB0, pB1, alB, alA, j + 1);
;   }
.LBB0_244:
	s_mov_b64 s[94:95], -1
	s_waitcnt lgkmcnt(0)
.LBB0_246:
.LBB0_248:
	v_add_f32_e32 v4, v213, v214
	v_fmac_f32_e32 v4, v186, v0
	v_add_f32_e32 v186, v2, v3
	s_add_u32 s0, s0, 0x40000
	v_fmac_f32_e32 v186, v4, v120
	s_addc_u32 s1, s1, 0
	v_add_u32_e32 v211, 0x200, v211
	s_add_i32 s63, s63, 0x8000
	s_addk_i32 s7, 0x80
	s_and_b64 vcc, exec, s[18:19]
	s_cbranch_vccnz .LBB0_250
	s_mov_b32 s4, s58
	s_mov_b32 s58, s6
	s_branch .LBB0_220
.Lmy_mb0_a1_1:
	s_waitcnt vmcnt(0) lgkmcnt(0)
	s_barrier
	s_branch .Lmy_mbj_a1_1

; #define SBAR() __builtin_amdgcn_sched_barrier(0)
; __device__ __forceinline__ s16x4 vtr(lds_cptr p) { return __builtin_bit_cast(s16x4, __builtin_amdgcn_ds_read_tr16_b64_v4i16((__attribute__((address_space(3))) v4i16_t*)p)); }
; #define PIN(x) asm volatile("" : "+v"(x))
; __device__ __forceinline__ void add_bias(f32x16& p0, f32x16& p1, const float* tb, int relb, int hi) {
;   const float* t = tb + relb + 4 * hi;
; #pragma unroll
;   for (int r = 0; r < 16; ++r) { p0[r] += t[(r & 3) + 8 * (r >> 2)]; p1[r] += t[32 + (r & 3) + 8 * (r >> 2)]; }
; }
; template <int DK, bool NOMAX> ...
;     ...
;   for (int d0 = 0; d0 < NS; ++d0) {
;     if (d0 == 0) { c0 = __builtin_amdgcn_mfma_f32_32x32x16_bf16(kf[0][0], qr[0], f32x16{}, 0, 0, 0); c1 = __builtin_amdgcn_mfma_f32_32x32x16_bf16(kf[0][1], qr[0], f32x16{}, 0, 0, 0); }
;     else { c0 = __builtin_amdgcn_mfma_f32_32x32x16_bf16(kf[d0 & 1][0], qr[d0], c0, 0, 0, 0); c1 = __builtin_amdgcn_mfma_f32_32x32x16_bf16(kf[d0 & 1][1], qr[d0], c1, 0, 0, 0); }
;     if (d0 + 2 < NS) KRD_(d0 & 1, d0 + 2);
;     if constexpr (NOMAX) { }
;     else {
; #pragma unroll
;     for (int r = d0 * RPS; r < (d0 + 1) * RPS; ++r) { p1[r] = __builtin_amdgcn_exp2f(p1[r]); psa += p0[r]; }
;     if (d0 > 0) {
; #pragma unroll
;       for (int r = (d0 - 1) * RPS; r < d0 * RPS; ++r) psb += p1[r]; } }
;     if constexpr (NOMAX) {
;       if (d0 == NS / 4 - 1) { PK4R(p0, 0, pa[0]); PIN(pa[0]); }
;       if (d0 == NS / 2 - 1) { PK4R(p0, 8, pa[1]); PIN(pa[1]); }
;       if (d0 == 3 * NS / 4 - 1) { PK4R(p1, 0, pa[2]); PIN(pa[2]); }
;       if (d0 == NS - 1) { PK4R(p1, 8, pa[3]); PIN(pa[3]); }
;     } else {
;     if (d0 == NS / 2 - 1) { PK4R(p0, 0, pa[0]); PIN(pa[0]); }
;     if (d0 == NS / 2) { PK4R(p0, 8, pa[1]); PIN(pa[1]); }
;     if (d0 == NS - 1) { PK4R(p1, 0, pa[2]); PIN(pa[2]); }
;     }
;     if (d0 == NS - 1) {
;       vl[0] = vtr(vp + v_rd_off(0, 0, 0)); vh[0] = vtr(vp + v_rd_off(0, 0, 1)); vl[1] = vtr(vp + v_rd_off(1, 0, 0)); vh[1] = vtr(vp + v_rd_off(1, 0, 1)); }
;     PIN(p1); PIN(psa); PIN(psb);
;     SBAR();
;   }
.LBB0_250:
	v_mfma_f32_32x32x16_bf16 v[128:143], v[116:119], v[156:159], 0
	v_add3_u32 v0, 0, v206, v190
	ds_read_b128 v[2:5], v0 offset:49152
	ds_read_b128 v[160:163], v0 offset:53248
	v_cvt_pk_bf16_f32 v96, v96, v97
	v_cvt_pk_bf16_f32 v97, v98, v99
	v_cvt_pk_bf16_f32 v98, v100, v101
	v_cvt_pk_bf16_f32 v99, v102, v103
	v_mov_b32_e32 v0, v1
	v_mfma_f32_32x32x16_bf16 v[112:127], v[112:115], v[156:159], 0
	v_permlane32_swap_b32_e32 v96, v98
	v_permlane32_swap_b32_e32 v97, v99
	v_mov_b32_e32 v14, v1
	v_mfma_f32_32x32x16_bf16 v[128:143], v[10:13], v[152:155], v[128:143]
	v_mfma_f32_32x32x16_bf16 v[112:127], v[6:9], v[152:155], v[112:127]
	v_add3_u32 v6, 0, v191, v190
	ds_read_b128 v[100:103], v6 offset:49152
	ds_read_b128 v[164:167], v6 offset:53248
	v_cvt_pk_bf16_f32 v10, v104, v105
	v_cvt_pk_bf16_f32 v11, v106, v107
	v_cvt_pk_bf16_f32 v12, v108, v109
	v_cvt_pk_bf16_f32 v13, v110, v111
	s_nop 0
	v_permlane32_swap_b32_e32 v10, v12
	v_permlane32_swap_b32_e32 v11, v13
	s_waitcnt lgkmcnt(3)
	v_mfma_f32_32x32x16_bf16 v[128:143], v[2:5], v[148:151], v[128:143]
	v_cvt_pk_bf16_f32 v6, v80, v81
	v_cvt_pk_bf16_f32 v7, v82, v83
	v_cvt_pk_bf16_f32 v8, v84, v85
	v_cvt_pk_bf16_f32 v9, v86, v87
	s_nop 0
	v_permlane32_swap_b32_e32 v6, v8
	s_waitcnt lgkmcnt(2)
	v_mfma_f32_32x32x16_bf16 v[112:127], v[160:163], v[148:151], v[112:127]
	v_permlane32_swap_b32_e32 v7, v9
	s_nop 0
	v_cvt_pk_bf16_f32 v2, v88, v89
	v_cvt_pk_bf16_f32 v3, v90, v91
	v_cvt_pk_bf16_f32 v4, v92, v93
	v_cvt_pk_bf16_f32 v5, v94, v95
	s_waitcnt lgkmcnt(1)
	v_mfma_f32_32x32x16_bf16 v[128:143], v[100:103], v[144:147], v[128:143]
	v_permlane32_swap_b32_e32 v2, v4
	v_permlane32_swap_b32_e32 v3, v5
	s_waitcnt vmcnt(0) lgkmcnt(0)
	s_barrier
	ds_read_b64_tr_b16 v[104:105], v187
	ds_read_b64_tr_b16 v[106:107], v187 offset:2048
	ds_read_b64_tr_b16 v[100:101], v187 offset:512
	ds_read_b64_tr_b16 v[102:103], v187 offset:2560
	s_waitcnt lgkmcnt(4)
	v_mfma_f32_32x32x16_bf16 v[112:127], v[164:167], v[144:147], v[112:127]
	s_nop 0
	v_mov_b32_e32 v0, v203
	s_and_saveexec_b64 s[0:1], s[44:45]
	s_cbranch_execz .LBB0_252
	v_sub_u32_e32 v0, 0x1fc0, v189
	s_add_i32 s3, 0, 0x1c800
	v_lshlrev_b32_e32 v0, 2, v0
	v_add3_u32 v0, s3, v0, v171
	v_add_u32_e32 v14, 0x400, v0
	v_add_u32_e32 v80, 0x480, v0
	ds_read2_b32 v[14:15], v14 offset1:1
	ds_read2_b32 v[80:81], v80 offset1:1
	v_add_u32_e32 v82, 0x408, v0
	v_add_u32_e32 v84, 0x488, v0
	v_add_u32_e32 v86, 0x420, v0
	v_add_u32_e32 v88, 0x4a0, v0
	v_add_u32_e32 v90, 0x428, v0
	v_add_u32_e32 v92, 0x4a8, v0
	v_add_u32_e32 v94, 0x440, v0
	v_add_u32_e32 v108, 0x4c0, v0
	v_add_u32_e32 v110, 0x448, v0
	v_add_u32_e32 v160, 0x4c8, v0
	v_add_u32_e32 v162, 0x460, v0
	v_add_u32_e32 v164, 0x4e0, v0
	v_add_u32_e32 v166, 0x468, v0
	v_add_u32_e32 v0, 0x4e8, v0
	ds_read2_b32 v[82:83], v82 offset1:1
	ds_read2_b32 v[84:85], v84 offset1:1
	ds_read2_b32 v[86:87], v86 offset1:1
	ds_read2_b32 v[88:89], v88 offset1:1
	ds_read2_b32 v[90:91], v90 offset1:1
	ds_read2_b32 v[92:93], v92 offset1:1
	ds_read2_b32 v[94:95], v94 offset1:1
	ds_read2_b32 v[108:109], v108 offset1:1
	ds_read2_b32 v[110:111], v110 offset1:1
	ds_read2_b32 v[160:161], v160 offset1:1
	ds_read2_b32 v[162:163], v162 offset1:1
	ds_read2_b32 v[164:165], v164 offset1:1
	ds_read2_b32 v[166:167], v166 offset1:1
	s_waitcnt lgkmcnt(0)
	v_pk_add_f32 v[128:129], v[128:129], v[14:15]
	ds_read2_b32 v[14:15], v0 offset1:1
	v_pk_add_f32 v[140:141], v[140:141], v[162:163]
	v_pk_add_f32 v[138:139], v[138:139], v[110:111]
	v_pk_add_f32 v[142:143], v[142:143], v[166:167]
	v_pk_add_f32 v[136:137], v[136:137], v[94:95]
	v_pk_add_f32 v[134:135], v[134:135], v[90:91]
	v_pk_add_f32 v[132:133], v[132:133], v[86:87]
	v_pk_add_f32 v[130:131], v[130:131], v[82:83]
	s_waitcnt lgkmcnt(0)
	v_pk_add_f32 v[126:127], v[126:127], v[14:15]
	v_pk_add_f32 v[124:125], v[124:125], v[164:165]
	v_pk_add_f32 v[122:123], v[122:123], v[160:161]
	v_pk_add_f32 v[120:121], v[120:121], v[108:109]
	v_pk_add_f32 v[118:119], v[118:119], v[92:93]
	v_pk_add_f32 v[116:117], v[116:117], v[88:89]
	v_pk_add_f32 v[114:115], v[114:115], v[84:85]
	v_pk_add_f32 v[112:113], v[112:113], v[80:81]
	v_mov_b32_e32 v0, 0

; #define SBAR() __builtin_amdgcn_sched_barrier(0)
; __device__ __forceinline__ s16x4 vtr(lds_cptr p) { return __builtin_bit_cast(s16x4, __builtin_amdgcn_ds_read_tr16_b64_v4i16((__attribute__((address_space(3))) v4i16_t*)p)); }
; #define PIN(x) asm volatile("" : "+v"(x))
; __device__ __forceinline__ void add_bias(f32x16& p0, f32x16& p1, const float* tb, int relb, int hi) {
;   const float* t = tb + relb + 4 * hi;
; #pragma unroll
;   for (int r = 0; r < 16; ++r) { p0[r] += t[(r & 3) + 8 * (r >> 2)]; p1[r] += t[32 + (r & 3) + 8 * (r >> 2)]; }
; }
; template <int DK, bool NOMAX> ...
;     ...
;   for (int d0 = 0; d0 < NS; ++d0) {
;     if (d0 == 0) { c0 = __builtin_amdgcn_mfma_f32_32x32x16_bf16(kf[0][0], qr[0], f32x16{}, 0, 0, 0); c1 = __builtin_amdgcn_mfma_f32_32x32x16_bf16(kf[0][1], qr[0], f32x16{}, 0, 0, 0); }
;     else { c0 = __builtin_amdgcn_mfma_f32_32x32x16_bf16(kf[d0 & 1][0], qr[d0], c0, 0, 0, 0); c1 = __builtin_amdgcn_mfma_f32_32x32x16_bf16(kf[d0 & 1][1], qr[d0], c1, 0, 0, 0); }
;     if (d0 + 2 < NS) KRD_(d0 & 1, d0 + 2);
;     if constexpr (NOMAX) { }
;     else {
; #pragma unroll
;     for (int r = d0 * RPS; r < (d0 + 1) * RPS; ++r) { p1[r] = __builtin_amdgcn_exp2f(p1[r]); psa += p0[r]; }
;     if (d0 > 0) {
; #pragma unroll
;       for (int r = (d0 - 1) * RPS; r < d0 * RPS; ++r) psb += p1[r]; } }
;     if constexpr (NOMAX) {
;       if (d0 == NS / 4 - 1) { PK4R(p0, 0, pa[0]); PIN(pa[0]); }
;       if (d0 == NS / 2 - 1) { PK4R(p0, 8, pa[1]); PIN(pa[1]); }
;       if (d0 == 3 * NS / 4 - 1) { PK4R(p1, 0, pa[2]); PIN(pa[2]); }
;       if (d0 == NS - 1) { PK4R(p1, 8, pa[3]); PIN(pa[3]); }
;     } else {
;     if (d0 == NS / 2 - 1) { PK4R(p0, 0, pa[0]); PIN(pa[0]); }
;     if (d0 == NS / 2) { PK4R(p0, 8, pa[1]); PIN(pa[1]); }
;     if (d0 == NS - 1) { PK4R(p1, 0, pa[2]); PIN(pa[2]); }
;     }
;     if (d0 == NS - 1) {
;       vl[0] = vtr(vp + v_rd_off(0, 0, 0)); vh[0] = vtr(vp + v_rd_off(0, 0, 1)); vl[1] = vtr(vp + v_rd_off(1, 0, 0)); vh[1] = vtr(vp + v_rd_off(1, 0, 1)); }
;     PIN(p1); PIN(psa); PIN(psb);
;     SBAR();
;   }
.LBB0_313:
	s_mov_b32 s58, s95
	s_mov_b32 s95, s4
	s_add_i32 s4, s63, 0xffff4000
	s_and_b32 s59, s4, 0xc000
	s_add_i32 s4, s59, 0
	v_add_u32_e32 v213, s95, v187
	s_waitcnt lgkmcnt(0)
	v_mfma_f32_32x32x16_bf16 v[128:143], v[116:119], v[156:159], 0
	v_add_u32_e32 v0, s4, v207
	ds_read_b128 v[2:5], v0
	ds_read_b128 v[164:167], v0 offset:4096
	v_cvt_pk_bf16_f32 v96, v96, v97
	v_cvt_pk_bf16_f32 v97, v98, v99
	v_cvt_pk_bf16_f32 v98, v100, v101
	v_cvt_pk_bf16_f32 v99, v102, v103
	v_mfma_f32_32x32x16_bf16 v[112:127], v[112:115], v[156:159], 0
	v_permlane32_swap_b32_e32 v96, v98
	v_permlane32_swap_b32_e32 v97, v99
	v_mfma_f32_32x32x16_bf16 v[128:143], v[10:13], v[152:155], v[128:143]
	v_mfma_f32_32x32x16_bf16 v[112:127], v[6:9], v[152:155], v[112:127]
	v_add_u32_e32 v6, s4, v208
	ds_read_b128 v[100:103], v6
	ds_read_b128 v[214:217], v6 offset:4096
	v_cvt_pk_bf16_f32 v10, v104, v105
	v_cvt_pk_bf16_f32 v11, v106, v107
	v_cvt_pk_bf16_f32 v12, v108, v109
	v_cvt_pk_bf16_f32 v13, v110, v111
	s_nop 0
	v_permlane32_swap_b32_e32 v10, v12
	v_permlane32_swap_b32_e32 v11, v13
	s_waitcnt lgkmcnt(3)
	v_mfma_f32_32x32x16_bf16 v[128:143], v[2:5], v[148:151], v[128:143]
	v_cvt_pk_bf16_f32 v6, v80, v81
	v_cvt_pk_bf16_f32 v7, v82, v83
	v_cvt_pk_bf16_f32 v8, v84, v85
	v_cvt_pk_bf16_f32 v9, v86, v87
	s_nop 0
	v_permlane32_swap_b32_e32 v6, v8
	s_waitcnt lgkmcnt(2)
	v_mfma_f32_32x32x16_bf16 v[112:127], v[164:167], v[148:151], v[112:127]
	v_permlane32_swap_b32_e32 v7, v9
	s_nop 0
	v_cvt_pk_bf16_f32 v2, v88, v89
	v_cvt_pk_bf16_f32 v3, v90, v91
	v_cvt_pk_bf16_f32 v4, v92, v93
	v_cvt_pk_bf16_f32 v5, v94, v95
	s_waitcnt lgkmcnt(1)
	v_mfma_f32_32x32x16_bf16 v[128:143], v[100:103], v[144:147], v[128:143]
	v_permlane32_swap_b32_e32 v2, v4
	v_permlane32_swap_b32_e32 v3, v5
	s_cmp_gt_i32 s96, 59
	s_cbranch_scc1 .Lmy_mb0_a2_1
	s_waitcnt vmcnt(3) lgkmcnt(0)
	s_barrier
.Lmy_mbj_a2_1:
	ds_read_b64_tr_b16 v[104:105], v213
	ds_read_b64_tr_b16 v[106:107], v213 offset:2048
	ds_read_b64_tr_b16 v[100:101], v213 offset:512
	ds_read_b64_tr_b16 v[102:103], v213 offset:2560
	s_waitcnt lgkmcnt(4)
	v_mfma_f32_32x32x16_bf16 v[112:127], v[214:217], v[144:147], v[112:127]
	v_add_u32_e32 v216, s94, v205
	v_add_u32_e32 v0, 0xffffffa1, v216
	v_cmp_gt_i32_e32 vcc, s67, v0
	v_mov_b32_e32 v215, v199
	s_and_saveexec_b64 s[4:5], vcc
	s_cbranch_execz .LBB0_317
	v_subrev_u32_e32 v0, 64, v216
	v_cmp_lt_i32_e32 vcc, s77, v0
	v_mov_b32_e32 v215, v198
	s_and_saveexec_b64 s[16:17], vcc
	s_cbranch_execz .LBB0_316
	ds_read2_b32 v[80:81], v211 offset1:1
	ds_read2_b32 v[82:83], v211 offset0:2 offset1:3
	ds_read2_b32 v[84:85], v211 offset0:8 offset1:9
	ds_read2_b32 v[86:87], v211 offset0:10 offset1:11
	ds_read2_b32 v[88:89], v211 offset0:16 offset1:17
	ds_read2_b32 v[90:91], v211 offset0:18 offset1:19
	ds_read2_b32 v[92:93], v211 offset0:24 offset1:25
	ds_read2_b32 v[94:95], v211 offset0:26 offset1:27
	ds_read2_b32 v[108:109], v211 offset0:32 offset1:33
	ds_read2_b32 v[110:111], v211 offset0:34 offset1:35
	ds_read2_b32 v[164:165], v211 offset0:40 offset1:41
	ds_read2_b32 v[166:167], v211 offset0:42 offset1:43
	s_waitcnt lgkmcnt(0)
	v_pk_add_f32 v[128:129], v[128:129], v[80:81]
	v_pk_add_f32 v[140:141], v[140:141], v[92:93]
	v_pk_add_f32 v[138:139], v[138:139], v[90:91]
	v_pk_add_f32 v[136:137], v[136:137], v[88:89]
	ds_read2_b32 v[80:81], v211 offset0:48 offset1:49
	ds_read2_b32 v[88:89], v211 offset0:50 offset1:51
	ds_read2_b32 v[90:91], v211 offset0:56 offset1:57
	ds_read2_b32 v[92:93], v211 offset0:58 offset1:59
	v_pk_add_f32 v[142:143], v[142:143], v[94:95]
	v_pk_add_f32 v[134:135], v[134:135], v[86:87]
	v_pk_add_f32 v[132:133], v[132:133], v[84:85]
	v_pk_add_f32 v[130:131], v[130:131], v[82:83]
	v_pk_add_f32 v[112:113], v[112:113], v[108:109]
	s_waitcnt lgkmcnt(0)
	v_pk_add_f32 v[126:127], v[126:127], v[92:93]
	v_pk_add_f32 v[124:125], v[124:125], v[90:91]
	v_pk_add_f32 v[122:123], v[122:123], v[88:89]
	v_pk_add_f32 v[120:121], v[120:121], v[80:81]
	v_pk_add_f32 v[118:119], v[118:119], v[166:167]
	v_pk_add_f32 v[116:117], v[116:117], v[164:165]
	v_pk_add_f32 v[114:115], v[114:115], v[110:111]
	v_mov_b32_e32 v215, 0

; #define SBAR() __builtin_amdgcn_sched_barrier(0)
; __device__ __forceinline__ s16x4 vtr(lds_cptr p) { return __builtin_bit_cast(s16x4, __builtin_amdgcn_ds_read_tr16_b64_v4i16((__attribute__((address_space(3))) v4i16_t*)p)); }
; #define PIN(x) asm volatile("" : "+v"(x))
; __device__ __forceinline__ void add_bias(f32x16& p0, f32x16& p1, const float* tb, int relb, int hi) {
;   const float* t = tb + relb + 4 * hi;
; #pragma unroll
;   for (int r = 0; r < 16; ++r) { p0[r] += t[(r & 3) + 8 * (r >> 2)]; p1[r] += t[32 + (r & 3) + 8 * (r >> 2)]; }
; }
; template <int DK, bool NOMAX> ...
;     ...
;   for (int d0 = 0; d0 < NS; ++d0) {
;     if (d0 == 0) { c0 = __builtin_amdgcn_mfma_f32_32x32x16_bf16(kf[0][0], qr[0], f32x16{}, 0, 0, 0); c1 = __builtin_amdgcn_mfma_f32_32x32x16_bf16(kf[0][1], qr[0], f32x16{}, 0, 0, 0); }
;     else { c0 = __builtin_amdgcn_mfma_f32_32x32x16_bf16(kf[d0 & 1][0], qr[d0], c0, 0, 0, 0); c1 = __builtin_amdgcn_mfma_f32_32x32x16_bf16(kf[d0 & 1][1], qr[d0], c1, 0, 0, 0); }
;     if (d0 + 2 < NS) KRD_(d0 & 1, d0 + 2);
;     if constexpr (NOMAX) { }
;     else {
; #pragma unroll
;     for (int r = d0 * RPS; r < (d0 + 1) * RPS; ++r) { p1[r] = __builtin_amdgcn_exp2f(p1[r]); psa += p0[r]; }
;     if (d0 > 0) {
; #pragma unroll
;       for (int r = (d0 - 1) * RPS; r < d0 * RPS; ++r) psb += p1[r]; } }
;     if constexpr (NOMAX) {
;       if (d0 == NS / 4 - 1) { PK4R(p0, 0, pa[0]); PIN(pa[0]); }
;       if (d0 == NS / 2 - 1) { PK4R(p0, 8, pa[1]); PIN(pa[1]); }
;       if (d0 == 3 * NS / 4 - 1) { PK4R(p1, 0, pa[2]); PIN(pa[2]); }
;       if (d0 == NS - 1) { PK4R(p1, 8, pa[3]); PIN(pa[3]); }
;     } else {
;     if (d0 == NS / 2 - 1) { PK4R(p0, 0, pa[0]); PIN(pa[0]); }
;     if (d0 == NS / 2) { PK4R(p0, 8, pa[1]); PIN(pa[1]); }
;     if (d0 == NS - 1) { PK4R(p1, 0, pa[2]); PIN(pa[2]); }
;     }
;     if (d0 == NS - 1) {
;       vl[0] = vtr(vp + v_rd_off(0, 0, 0)); vh[0] = vtr(vp + v_rd_off(0, 0, 1)); vl[1] = vtr(vp + v_rd_off(1, 0, 0)); vh[1] = vtr(vp + v_rd_off(1, 0, 1)); }
;     PIN(p1); PIN(psa); PIN(psb);
;     SBAR();
;   }
.LBB0_325:
.LBB0_327:
	v_add_u32_e32 v217, s58, v187
	v_mfma_f32_32x32x16_bf16 v[96:111], v[80:83], v[156:159], 0
	v_add_u32_e32 v212, s18, v207
	ds_read_b128 v[2:5], v212
	ds_read_b128 v[218:221], v212 offset:4096
	v_cvt_pk_bf16_f32 v128, v128, v129
	v_cvt_pk_bf16_f32 v129, v130, v131
	v_cvt_pk_bf16_f32 v130, v132, v133
	v_cvt_pk_bf16_f32 v131, v134, v135
	v_mfma_f32_32x32x16_bf16 v[80:95], v[84:87], v[156:159], 0
	v_permlane32_swap_b32_e32 v128, v130
	v_permlane32_swap_b32_e32 v129, v131
	v_mfma_f32_32x32x16_bf16 v[96:111], v[6:9], v[152:155], v[96:111]
	v_add_u32_e32 v6, s18, v208
	ds_read_b128 v[132:135], v6
	ds_read_b128 v[222:225], v6 offset:4096
	v_mfma_f32_32x32x16_bf16 v[80:95], v[10:13], v[152:155], v[80:95]
	v_cvt_pk_bf16_f32 v10, v136, v137
	v_cvt_pk_bf16_f32 v11, v138, v139
	v_cvt_pk_bf16_f32 v12, v140, v141
	v_cvt_pk_bf16_f32 v13, v142, v143
	s_nop 0
	v_permlane32_swap_b32_e32 v10, v12
	v_permlane32_swap_b32_e32 v11, v13
	s_waitcnt lgkmcnt(3)
	v_mfma_f32_32x32x16_bf16 v[96:111], v[2:5], v[148:151], v[96:111]
	v_cvt_pk_bf16_f32 v6, v112, v113
	v_cvt_pk_bf16_f32 v7, v114, v115
	v_cvt_pk_bf16_f32 v8, v116, v117
	v_cvt_pk_bf16_f32 v9, v118, v119
	s_nop 0
	v_permlane32_swap_b32_e32 v6, v8
	s_waitcnt lgkmcnt(2)
	v_mfma_f32_32x32x16_bf16 v[80:95], v[218:221], v[148:151], v[80:95]
	v_permlane32_swap_b32_e32 v7, v9
	s_nop 0
	v_cvt_pk_bf16_f32 v2, v120, v121
	v_cvt_pk_bf16_f32 v3, v122, v123
	v_cvt_pk_bf16_f32 v4, v124, v125
	v_cvt_pk_bf16_f32 v5, v126, v127
	s_waitcnt lgkmcnt(1)
	v_mfma_f32_32x32x16_bf16 v[96:111], v[132:135], v[144:147], v[96:111]
	v_permlane32_swap_b32_e32 v2, v4
	v_permlane32_swap_b32_e32 v3, v5
	s_cmp_gt_i32 s96, 60
	s_cbranch_scc1 .Lmy_mb0_a2_2
	s_waitcnt vmcnt(3) lgkmcnt(0)
	s_barrier
.Lmy_mbj_a2_2:
	ds_read_b64_tr_b16 v[136:137], v217
	ds_read_b64_tr_b16 v[138:139], v217 offset:2048
	ds_read_b64_tr_b16 v[132:133], v217 offset:512
	ds_read_b64_tr_b16 v[134:135], v217 offset:2560
	s_waitcnt lgkmcnt(4)
	v_mfma_f32_32x32x16_bf16 v[80:95], v[222:225], v[144:147], v[80:95]
	v_subrev_u32_e32 v112, 31, v216
	v_cmp_gt_i32_e32 vcc, s67, v112
	v_mov_b32_e32 v212, v199
	s_and_saveexec_b64 s[4:5], vcc
	s_cbranch_execz .LBB0_331
	v_cmp_ge_i32_e32 vcc, s94, v181
	v_mov_b32_e32 v212, v198
	s_and_saveexec_b64 s[18:19], vcc
	s_cbranch_execz .LBB0_330
	ds_read2_b32 v[112:113], v211 offset0:64 offset1:65
	ds_read2_b32 v[114:115], v211 offset0:66 offset1:67
	ds_read2_b32 v[116:117], v211 offset0:72 offset1:73
	ds_read2_b32 v[118:119], v211 offset0:74 offset1:75
	ds_read2_b32 v[120:121], v211 offset0:80 offset1:81
	ds_read2_b32 v[122:123], v211 offset0:82 offset1:83
	ds_read2_b32 v[124:125], v211 offset0:88 offset1:89
	ds_read2_b32 v[126:127], v211 offset0:90 offset1:91
	ds_read2_b32 v[140:141], v211 offset0:96 offset1:97
	ds_read2_b32 v[142:143], v211 offset0:98 offset1:99
	ds_read2_b32 v[218:219], v211 offset0:104 offset1:105
	ds_read2_b32 v[220:221], v211 offset0:106 offset1:107
	s_waitcnt lgkmcnt(0)
	v_pk_add_f32 v[96:97], v[96:97], v[112:113]
	v_pk_add_f32 v[108:109], v[108:109], v[124:125]
	v_pk_add_f32 v[106:107], v[106:107], v[122:123]
	v_pk_add_f32 v[104:105], v[104:105], v[120:121]
	ds_read2_b32 v[112:113], v211 offset0:112 offset1:113
	ds_read2_b32 v[120:121], v211 offset0:114 offset1:115
	ds_read2_b32 v[122:123], v211 offset0:120 offset1:121
	ds_read2_b32 v[124:125], v211 offset0:122 offset1:123
	v_pk_add_f32 v[110:111], v[110:111], v[126:127]
	v_pk_add_f32 v[102:103], v[102:103], v[118:119]
	v_pk_add_f32 v[100:101], v[100:101], v[116:117]
	v_pk_add_f32 v[98:99], v[98:99], v[114:115]
	v_pk_add_f32 v[80:81], v[80:81], v[140:141]
	s_waitcnt lgkmcnt(0)
	v_pk_add_f32 v[94:95], v[94:95], v[124:125]
	v_pk_add_f32 v[92:93], v[92:93], v[122:123]
	v_pk_add_f32 v[90:91], v[90:91], v[120:121]
	v_pk_add_f32 v[88:89], v[88:89], v[112:113]
	v_pk_add_f32 v[86:87], v[86:87], v[220:221]
	v_pk_add_f32 v[84:85], v[84:85], v[218:219]
	v_pk_add_f32 v[82:83], v[82:83], v[142:143]
	v_mov_b32_e32 v212, 0

; template <int DK, int LDK, bool BIAS, bool NOMAX> ...
;     ...
;   for (int j = 1; j + 1 < NT; j += 2) {
;     STEPT(pB0, pB1, pA0, pA1, alA, alB, j);
;     STEPT(pA0, pA1, pB0, pB1, alB, alA, j + 1);
;   }
.LBB0_337:
	s_mov_b64 s[18:19], -1
	s_waitcnt lgkmcnt(0)
.LBB0_339:
.LBB0_341:
	v_add_f32_e32 v4, v213, v214
	v_fmac_f32_e32 v4, v186, v0
	v_add_f32_e32 v186, v2, v3
	s_add_u32 s0, s0, 0x40000
	v_fmac_f32_e32 v186, v4, v120
	s_addc_u32 s1, s1, 0
	v_add_u32_e32 v211, 0x200, v211
	s_add_i32 s63, s63, 0x8000
	s_addk_i32 s94, 0x80
	s_and_b64 vcc, exec, s[16:17]
	s_cbranch_vccnz .LBB0_343
	s_mov_b32 s4, s97
	s_mov_b32 s97, s58
	s_branch .LBB0_313

; #define SBAR() __builtin_amdgcn_sched_barrier(0)
; __device__ __forceinline__ s16x4 vtr(lds_cptr p) { return __builtin_bit_cast(s16x4, __builtin_amdgcn_ds_read_tr16_b64_v4i16((__attribute__((address_space(3))) v4i16_t*)p)); }
; #define PIN(x) asm volatile("" : "+v"(x))
; __device__ __forceinline__ void add_bias(f32x16& p0, f32x16& p1, const float* tb, int relb, int hi) {
;   const float* t = tb + relb + 4 * hi;
; #pragma unroll
;   for (int r = 0; r < 16; ++r) { p0[r] += t[(r & 3) + 8 * (r >> 2)]; p1[r] += t[32 + (r & 3) + 8 * (r >> 2)]; }
; }
; template <int DK, bool NOMAX> ...
;     ...
;   for (int d0 = 0; d0 < NS; ++d0) {
;     if (d0 == 0) { c0 = __builtin_amdgcn_mfma_f32_32x32x16_bf16(kf[0][0], qr[0], f32x16{}, 0, 0, 0); c1 = __builtin_amdgcn_mfma_f32_32x32x16_bf16(kf[0][1], qr[0], f32x16{}, 0, 0, 0); }
;     else { c0 = __builtin_amdgcn_mfma_f32_32x32x16_bf16(kf[d0 & 1][0], qr[d0], c0, 0, 0, 0); c1 = __builtin_amdgcn_mfma_f32_32x32x16_bf16(kf[d0 & 1][1], qr[d0], c1, 0, 0, 0); }
;     if (d0 + 2 < NS) KRD_(d0 & 1, d0 + 2);
;     if constexpr (NOMAX) { }
;     else {
; #pragma unroll
;     for (int r = d0 * RPS; r < (d0 + 1) * RPS; ++r) { p1[r] = __builtin_amdgcn_exp2f(p1[r]); psa += p0[r]; }
;     if (d0 > 0) {
; #pragma unroll
;       for (int r = (d0 - 1) * RPS; r < d0 * RPS; ++r) psb += p1[r]; } }
;     if constexpr (NOMAX) {
;       if (d0 == NS / 4 - 1) { PK4R(p0, 0, pa[0]); PIN(pa[0]); }
;       if (d0 == NS / 2 - 1) { PK4R(p0, 8, pa[1]); PIN(pa[1]); }
;       if (d0 == 3 * NS / 4 - 1) { PK4R(p1, 0, pa[2]); PIN(pa[2]); }
;       if (d0 == NS - 1) { PK4R(p1, 8, pa[3]); PIN(pa[3]); }
;     } else {
;     if (d0 == NS / 2 - 1) { PK4R(p0, 0, pa[0]); PIN(pa[0]); }
;     if (d0 == NS / 2) { PK4R(p0, 8, pa[1]); PIN(pa[1]); }
;     if (d0 == NS - 1) { PK4R(p1, 0, pa[2]); PIN(pa[2]); }
;     }
;     if (d0 == NS - 1) {
;       vl[0] = vtr(vp + v_rd_off(0, 0, 0)); vh[0] = vtr(vp + v_rd_off(0, 0, 1)); vl[1] = vtr(vp + v_rd_off(1, 0, 0)); vh[1] = vtr(vp + v_rd_off(1, 0, 1)); }
;     PIN(p1); PIN(psa); PIN(psb);
;     SBAR();
;   }
.LBB0_343:
	v_mfma_f32_32x32x16_bf16 v[128:143], v[116:119], v[156:159], 0
	v_add3_u32 v0, 0, v206, v190
	ds_read_b128 v[2:5], v0 offset:49152
	ds_read_b128 v[160:163], v0 offset:53248
	v_cvt_pk_bf16_f32 v96, v96, v97
	v_cvt_pk_bf16_f32 v97, v98, v99
	v_cvt_pk_bf16_f32 v98, v100, v101
	v_cvt_pk_bf16_f32 v99, v102, v103
	v_mov_b32_e32 v0, v1
	v_mfma_f32_32x32x16_bf16 v[112:127], v[112:115], v[156:159], 0
	v_permlane32_swap_b32_e32 v96, v98
	v_permlane32_swap_b32_e32 v97, v99
	v_mov_b32_e32 v14, v1
	v_mfma_f32_32x32x16_bf16 v[128:143], v[10:13], v[152:155], v[128:143]
	v_mfma_f32_32x32x16_bf16 v[112:127], v[6:9], v[152:155], v[112:127]
	v_add3_u32 v6, 0, v191, v190
	ds_read_b128 v[100:103], v6 offset:49152
	ds_read_b128 v[164:167], v6 offset:53248
	v_cvt_pk_bf16_f32 v10, v104, v105
	v_cvt_pk_bf16_f32 v11, v106, v107
	v_cvt_pk_bf16_f32 v12, v108, v109
	v_cvt_pk_bf16_f32 v13, v110, v111
	s_nop 0
	v_permlane32_swap_b32_e32 v10, v12
	v_permlane32_swap_b32_e32 v11, v13
	s_waitcnt lgkmcnt(3)
	v_mfma_f32_32x32x16_bf16 v[128:143], v[2:5], v[148:151], v[128:143]
	v_cvt_pk_bf16_f32 v6, v80, v81
	v_cvt_pk_bf16_f32 v7, v82, v83
	v_cvt_pk_bf16_f32 v8, v84, v85
	v_cvt_pk_bf16_f32 v9, v86, v87
	s_nop 0
	v_permlane32_swap_b32_e32 v6, v8
	s_waitcnt lgkmcnt(2)
	v_mfma_f32_32x32x16_bf16 v[112:127], v[160:163], v[148:151], v[112:127]
	v_permlane32_swap_b32_e32 v7, v9
	s_nop 0
	v_cvt_pk_bf16_f32 v2, v88, v89
	v_cvt_pk_bf16_f32 v3, v90, v91
	v_cvt_pk_bf16_f32 v4, v92, v93
	v_cvt_pk_bf16_f32 v5, v94, v95
	s_waitcnt lgkmcnt(1)
	v_mfma_f32_32x32x16_bf16 v[128:143], v[100:103], v[144:147], v[128:143]
	v_permlane32_swap_b32_e32 v2, v4
	v_permlane32_swap_b32_e32 v3, v5
	s_waitcnt vmcnt(0) lgkmcnt(0)
	s_barrier
	ds_read_b64_tr_b16 v[104:105], v187 offset:32768
	ds_read_b64_tr_b16 v[106:107], v187 offset:34816
	ds_read_b64_tr_b16 v[100:101], v187 offset:33280
	ds_read_b64_tr_b16 v[102:103], v187 offset:35328
	s_waitcnt lgkmcnt(4)
	v_mfma_f32_32x32x16_bf16 v[112:127], v[164:167], v[144:147], v[112:127]
	s_nop 0
	v_mov_b32_e32 v0, v203
	s_and_saveexec_b64 s[0:1], s[44:45]
	s_cbranch_execz .LBB0_345
	v_sub_u32_e32 v0, 0xfc0, v189
	s_add_i32 s3, 0, 0x1c800
	v_lshlrev_b32_e32 v0, 2, v0
	v_add3_u32 v0, s3, v0, v170
	v_add_u32_e32 v14, 0x400, v0
	v_add_u32_e32 v80, 0x480, v0
	ds_read2_b32 v[14:15], v14 offset1:1
	ds_read2_b32 v[80:81], v80 offset1:1
	v_add_u32_e32 v82, 0x408, v0
	v_add_u32_e32 v84, 0x488, v0
	v_add_u32_e32 v86, 0x420, v0
	v_add_u32_e32 v88, 0x4a0, v0
	v_add_u32_e32 v90, 0x428, v0
	v_add_u32_e32 v92, 0x4a8, v0
	v_add_u32_e32 v94, 0x440, v0
	v_add_u32_e32 v108, 0x4c0, v0
	v_add_u32_e32 v110, 0x448, v0
	v_add_u32_e32 v160, 0x4c8, v0
	v_add_u32_e32 v162, 0x460, v0
	v_add_u32_e32 v164, 0x4e0, v0
	v_add_u32_e32 v166, 0x468, v0
	v_add_u32_e32 v0, 0x4e8, v0
	ds_read2_b32 v[82:83], v82 offset1:1
	ds_read2_b32 v[84:85], v84 offset1:1
	ds_read2_b32 v[86:87], v86 offset1:1
	ds_read2_b32 v[88:89], v88 offset1:1
	ds_read2_b32 v[90:91], v90 offset1:1
	ds_read2_b32 v[92:93], v92 offset1:1
	ds_read2_b32 v[94:95], v94 offset1:1
	ds_read2_b32 v[108:109], v108 offset1:1
	ds_read2_b32 v[110:111], v110 offset1:1
	ds_read2_b32 v[160:161], v160 offset1:1
	ds_read2_b32 v[162:163], v162 offset1:1
	ds_read2_b32 v[164:165], v164 offset1:1
	ds_read2_b32 v[166:167], v166 offset1:1
	s_waitcnt lgkmcnt(0)
	v_pk_add_f32 v[128:129], v[128:129], v[14:15]
	ds_read2_b32 v[14:15], v0 offset1:1
	v_pk_add_f32 v[140:141], v[140:141], v[162:163]
	v_pk_add_f32 v[138:139], v[138:139], v[110:111]
	v_pk_add_f32 v[142:143], v[142:143], v[166:167]
	v_pk_add_f32 v[136:137], v[136:137], v[94:95]
	v_pk_add_f32 v[134:135], v[134:135], v[90:91]
	v_pk_add_f32 v[132:133], v[132:133], v[86:87]
	v_pk_add_f32 v[130:131], v[130:131], v[82:83]
	s_waitcnt lgkmcnt(0)
	v_pk_add_f32 v[126:127], v[126:127], v[14:15]
	v_pk_add_f32 v[124:125], v[124:125], v[164:165]
	v_pk_add_f32 v[122:123], v[122:123], v[160:161]
	v_pk_add_f32 v[120:121], v[120:121], v[108:109]
	v_pk_add_f32 v[118:119], v[118:119], v[92:93]
	v_pk_add_f32 v[116:117], v[116:117], v[88:89]
	v_pk_add_f32 v[114:115], v[114:115], v[84:85]
	v_pk_add_f32 v[112:113], v[112:113], v[80:81]
	v_mov_b32_e32 v0, 0

; template <int DK, bool NOMAX> ...
;     ...
;   for (int d0 = 0; d0 < NS; ++d0) {
;     if (d0 == 0) { c0 = __builtin_amdgcn_mfma_f32_32x32x16_bf16(kf[0][0], qr[0], f32x16{}, 0, 0, 0); c1 = __builtin_amdgcn_mfma_f32_32x32x16_bf16(kf[0][1], qr[0], f32x16{}, 0, 0, 0); }
;     else { c0 = __builtin_amdgcn_mfma_f32_32x32x16_bf16(kf[d0 & 1][0], qr[d0], c0, 0, 0, 0); c1 = __builtin_amdgcn_mfma_f32_32x32x16_bf16(kf[d0 & 1][1], qr[d0], c1, 0, 0, 0); }
;     if (d0 + 2 < NS) KRD_(d0 & 1, d0 + 2);
;     if constexpr (NOMAX) { }
;     else {
; #pragma unroll
;     for (int r = d0 * RPS; r < (d0 + 1) * RPS; ++r) { p1[r] = __builtin_amdgcn_exp2f(p1[r]); psa += p0[r]; }
;     if (d0 > 0) {
; #pragma unroll
;       for (int r = (d0 - 1) * RPS; r < d0 * RPS; ++r) psb += p1[r]; } }
;     if constexpr (NOMAX) {
;       if (d0 == NS / 4 - 1) { PK4R(p0, 0, pa[0]); PIN(pa[0]); }
;       if (d0 == NS / 2 - 1) { PK4R(p0, 8, pa[1]); PIN(pa[1]); }
;       if (d0 == 3 * NS / 4 - 1) { PK4R(p1, 0, pa[2]); PIN(pa[2]); }
;       if (d0 == NS - 1) { PK4R(p1, 8, pa[3]); PIN(pa[3]); }
;     } else {
;     if (d0 == NS / 2 - 1) { PK4R(p0, 0, pa[0]); PIN(pa[0]); }
;     if (d0 == NS / 2) { PK4R(p0, 8, pa[1]); PIN(pa[1]); }
;     if (d0 == NS - 1) { PK4R(p1, 0, pa[2]); PIN(pa[2]); }
;     }
;     if (d0 == NS - 1) {
;       vl[0] = vtr(vp + v_rd_off(0, 0, 0)); vh[0] = vtr(vp + v_rd_off(0, 0, 1)); vl[1] = vtr(vp + v_rd_off(1, 0, 0)); vh[1] = vtr(vp + v_rd_off(1, 0, 1)); }
;     PIN(p1); PIN(psa); PIN(psb);
;     SBAR();
;   }
; template <int DK, bool NOMAX> ...
;     ...
;   for (int i = 0; i < 16; ++i) {
;     if (i + 2 < 16) VRD_((i + 2) % 3, i + 2);
;     if (i == 1) { if (dk) __builtin_amdgcn_global_load_lds((const unsigned*)gk0, lk, 16, 0, 0); }
;     if (i == 3) { if constexpr (DK == 128) { if (dk) __builtin_amdgcn_global_load_lds((const unsigned*)gk1, (lds_up)((lds_cp)lk + 8192), 16, 0, 0); } }
;     if (i == 5) { if (dv) __builtin_amdgcn_global_load_lds((const unsigned*)gv0, lv, 16, 0, 0); }
;     if (i == 7) { if (dv) __builtin_amdgcn_global_load_lds((const unsigned*)gv1, (lds_up)((lds_cp)lv + 8192), 16, 0, 0); }
;     if (i == 12 || i == 13) { const int cb_ = ((i - 12) * 16 + hi * 8) * 2;
;       if constexpr (DK == 128) { kf[i - 12][0] = *reinterpret_cast<const bf16x8*>(Kn + KSWZ128(r32, cb_)); kf[i - 12][1] = *reinterpret_cast<const bf16x8*>(Kn + KSWZ128(32 + r32, cb_)); }
.LBB0_402:
	s_mov_b32 s17, s14
	s_mov_b32 s14, s8
	s_add_i32 s8, s18, 0xffffc000
	s_and_b32 s38, s8, 0xc000
	s_add_i32 s8, s38, 0
	v_add_u32_e32 v0, s14, v204
	s_waitcnt lgkmcnt(0)
	v_mfma_f32_32x32x16_bf16 v[114:129], v[102:105], v[158:161], 0
	v_add_u32_e32 v188, s8, v218
	ds_read_b128 v[184:187], v188
	ds_read_b128 v[188:191], v188 offset:8192
	v_mfma_f32_32x32x16_bf16 v[98:113], v[98:101], v[158:161], 0
	v_mfma_f32_32x32x16_bf16 v[114:129], v[166:169], v[154:157], v[114:129]
	v_mfma_f32_32x32x16_bf16 v[98:113], v[162:165], v[154:157], v[98:113]
	v_add_u32_e32 v162, s8, v219
	ds_read_b128 v[166:169], v162
	ds_read_b128 v[226:229], v162 offset:8192
	v_cvt_pk_bf16_f32 v162, v82, v83
	v_cvt_pk_bf16_f32 v163, v84, v85
	v_cvt_pk_bf16_f32 v164, v86, v87
	v_cvt_pk_bf16_f32 v165, v88, v89
	s_nop 0
	v_permlane32_swap_b32_e32 v162, v164
	v_permlane32_swap_b32_e32 v163, v165
	s_waitcnt lgkmcnt(3)
	v_mfma_f32_32x32x16_bf16 v[114:129], v[184:187], v[150:153], v[114:129]
	v_add_u32_e32 v86, s8, v220
	ds_read_b128 v[82:85], v86
	ds_read_b128 v[86:89], v86 offset:8192
	s_waitcnt lgkmcnt(4)
	v_mfma_f32_32x32x16_bf16 v[98:113], v[188:191], v[150:153], v[98:113]
	s_waitcnt lgkmcnt(3)
	v_mfma_f32_32x32x16_bf16 v[114:129], v[166:169], v[146:149], v[114:129]
	v_add_u32_e32 v184, s8, v221
	ds_read_b128 v[166:169], v184
	ds_read_b128 v[184:187], v184 offset:8192
	v_cvt_pk_bf16_f32 v90, v90, v91
	v_cvt_pk_bf16_f32 v91, v92, v93
	v_cvt_pk_bf16_f32 v92, v94, v95
	v_cvt_pk_bf16_f32 v93, v96, v97
	s_waitcnt lgkmcnt(4)
	v_mfma_f32_32x32x16_bf16 v[98:113], v[226:229], v[146:149], v[98:113]
	v_permlane32_swap_b32_e32 v90, v92
	v_permlane32_swap_b32_e32 v91, v93
	s_waitcnt lgkmcnt(3)
	v_mfma_f32_32x32x16_bf16 v[114:129], v[82:85], v[142:145], v[114:129]
	s_waitcnt lgkmcnt(2)
	v_mfma_f32_32x32x16_bf16 v[98:113], v[86:89], v[142:145], v[98:113]
	v_add_u32_e32 v86, s8, v222
	ds_read_b128 v[82:85], v86
	ds_read_b128 v[94:97], v86 offset:8192
	s_waitcnt lgkmcnt(3)
	v_mfma_f32_32x32x16_bf16 v[114:129], v[166:169], v[138:141], v[114:129]
	v_add_u32_e32 v86, s8, v223
	s_waitcnt lgkmcnt(2)
	v_mfma_f32_32x32x16_bf16 v[98:113], v[184:187], v[138:141], v[98:113]
	ds_read_b128 v[166:169], v86
	ds_read_b128 v[184:187], v86 offset:8192
	v_cvt_pk_bf16_f32 v86, v66, v67
	v_cvt_pk_bf16_f32 v87, v68, v69
	v_cvt_pk_bf16_f32 v88, v70, v71
	v_cvt_pk_bf16_f32 v89, v72, v73
	s_nop 0
	v_permlane32_swap_b32_e32 v86, v88
	v_permlane32_swap_b32_e32 v87, v89
	s_waitcnt lgkmcnt(3)
	v_mfma_f32_32x32x16_bf16 v[114:129], v[82:85], v[130:133], v[114:129]
	s_waitcnt lgkmcnt(2)
	v_mfma_f32_32x32x16_bf16 v[98:113], v[94:97], v[130:133], v[98:113]
	v_cvt_pk_bf16_f32 v82, v74, v75
	v_cvt_pk_bf16_f32 v83, v76, v77
	v_cvt_pk_bf16_f32 v84, v78, v79
	v_cvt_pk_bf16_f32 v85, v80, v81
	s_waitcnt lgkmcnt(1)
	v_mfma_f32_32x32x16_bf16 v[114:129], v[166:169], v[134:137], v[114:129]
	v_permlane32_swap_b32_e32 v82, v84
	v_permlane32_swap_b32_e32 v83, v85
	s_cmpk_gt_i32 s15, 0x7d
	s_cbranch_scc1 .Lmy_mb0_b1_1
	s_waitcnt vmcnt(4) lgkmcnt(0)
	s_barrier
.Lmy_mbj_b1_1:
	ds_read_b64_tr_b16 v[166:167], v0
	ds_read_b64_tr_b16 v[168:169], v0 offset:2048
	ds_read_b64_tr_b16 v[94:95], v0 offset:512
	ds_read_b64_tr_b16 v[96:97], v0 offset:2560
	s_waitcnt lgkmcnt(4)
	v_mfma_f32_32x32x16_bf16 v[98:113], v[184:187], v[134:137], v[98:113]
	s_cmpk_lt_u32 s15, 0x7d
	s_cselect_b64 s[10:11], -1, 0
	s_cmpk_gt_u32 s15, 0x7c
	s_cselect_b64 s[8:9], -1, 0
	s_add_i32 s19, s18, 0x8000
	s_and_b32 s12, s19, 0xc000
	ds_read_b64_tr_b16 v[70:71], v0 offset:1024
	ds_read_b64_tr_b16 v[72:73], v0 offset:3072
	s_waitcnt lgkmcnt(4)
	v_mfma_f32_32x32x16_bf16 v[50:65], v[162:165], v[166:169], v[50:65]
	v_exp_f32_e32 v114, v114
	s_nop 0
	v_exp_f32_e32 v98, v98
	ds_read_b64_tr_b16 v[66:67], v0 offset:1536
	ds_read_b64_tr_b16 v[68:69], v0 offset:3584
	s_and_b64 vcc, exec, s[8:9]
	s_cbranch_vccnz .LBB0_404
	s_add_u32 vcc_lo, s0, s50
	s_addc_u32 vcc_hi, s1, s51
	s_add_i32 m0, s2, s12
	s_nop 0
	global_load_lds_dwordx4 v182, vcc

; template <int DK, bool NOMAX> ...
;     ...
;   for (int i = 0; i < 16; ++i) {
;     if (i + 2 < 16) VRD_((i + 2) % 3, i + 2);
;     if (i == 1) { if (dk) __builtin_amdgcn_global_load_lds((const unsigned*)gk0, lk, 16, 0, 0); }
;     if (i == 3) { if constexpr (DK == 128) { if (dk) __builtin_amdgcn_global_load_lds((const unsigned*)gk1, (lds_up)((lds_cp)lk + 8192), 16, 0, 0); } }
;     if (i == 5) { if (dv) __builtin_amdgcn_global_load_lds((const unsigned*)gv0, lv, 16, 0, 0); }
;     if (i == 7) { if (dv) __builtin_amdgcn_global_load_lds((const unsigned*)gv1, (lds_up)((lds_cp)lv + 8192), 16, 0, 0); }
;     if (i == 12 || i == 13) { const int cb_ = ((i - 12) * 16 + hi * 8) * 2;
;       if constexpr (DK == 128) { kf[i - 12][0] = *reinterpret_cast<const bf16x8*>(Kn + KSWZ128(r32, cb_)); kf[i - 12][1] = *reinterpret_cast<const bf16x8*>(Kn + KSWZ128(32 + r32, cb_)); }
;       else { kf[i - 12][0] = *reinterpret_cast<const bf16x8*>(Kn + KSWZ64(r32, cb_)); kf[i - 12][1] = *reinterpret_cast<const bf16x8*>(Kn + KSWZ64(32 + r32, cb_)); } }
;     SBAR();
;     o[i & 3] = __builtin_amdgcn_mfma_f32_32x32x16_bf16(pa[i >> 2], VFR_(i % 3), o[i & 3], 0, 0, 0);
;     if constexpr (NOMAX) { c0[i] = __builtin_amdgcn_exp2f(c0[i]); c1[i] = __builtin_amdgcn_exp2f(c1[i]); if (i > 0) { psa += c0[i - 1]; psb += c1[i - 1]; } PIN(c0); PIN(c1); PIN(psa); PIN(psb); }
;     else {
;     if (i == 0) { ma = max3f(c0[0], c0[1], c1[0]); mb = max3f(c0[2], c0[3], c1[1]); ma = max3f(ma, c1[2], c1[3]); }
;     if (i >= 1 && i <= 3) { const int r = 4 * i; ma = max3f(ma, c0[r], c0[r + 1]); mb = max3f(mb, c0[r + 2], c0[r + 3]); ma = max3f(ma, c1[r], c1[r + 1]); mb = max3f(mb, c1[r + 2], c1[r + 3]); }
;     if (i == 4) { float pmax = fmaxf(ma, mb);
;       { auto rr = __builtin_amdgcn_permlane32_swap(__float_as_uint(pmax), __float_as_uint(pmax), false, false);
;         pmax = fmaxf(__uint_as_float(rr[0]), __uint_as_float(rr[1])); }
;       pmax += cb;
;       const bool keep = __all(pmax - m_reg <= THR2);
;       const float mn = keep ? m_reg : fmaxf(m_reg, pmax);
;       alpha = __builtin_amdgcn_exp2f(m_reg - mn); m_reg = mn; mnC = cb - mn; }
;     if (i >= 5 && i <= 8) { const int r = 4 * (i - 5);
; #pragma unroll
;       for (int q = 0; q < 4; ++q) { c0[r + q] += mnC; c1[r + q] += mnC; } }
;     if (i >= 9) { const int r0 = (i - 9) * 2 + (i > 14 ? 1 : 0), n = i >= 14 ? 3 : 2;
; #pragma unroll
.LBB0_406:
	s_and_b32 s10, s18, 0xc000
	s_add_i32 s12, s10, 0
	s_waitcnt lgkmcnt(4)
	v_mfma_f32_32x32x16_bf16 v[2:17], v[162:165], v[66:69], v[2:17]
	v_exp_f32_e32 v117, v117
	v_exp_f32_e32 v101, v101
	v_add_f32_e32 v79, v100, v79
	v_add_f32_e32 v78, v116, v78
	ds_read_b64_tr_b16 v[66:67], v0 offset:5120
	ds_read_b64_tr_b16 v[68:69], v0 offset:7168
	s_waitcnt lgkmcnt(4)
	v_mfma_f32_32x32x16_bf16 v[50:65], v[90:93], v[74:77], v[50:65]
	v_exp_f32_e32 v118, v118
	v_exp_f32_e32 v102, v102
	v_add_f32_e32 v79, v101, v79
	v_add_f32_e32 v78, v117, v78
	s_add_u32 vcc_lo, s0, s60
	s_addc_u32 vcc_hi, s1, s61
	s_add_i32 s10, s3, s16
	s_mov_b32 m0, s10
	ds_read_b64_tr_b16 v[74:75], v0 offset:5632
	ds_read_b64_tr_b16 v[76:77], v0 offset:7680
	global_load_lds_dwordx4 v172, vcc
	s_waitcnt lgkmcnt(4)
	v_mfma_f32_32x32x16_bf16 v[34:49], v[90:93], v[70:73], v[34:49]
	v_exp_f32_e32 v119, v119
	v_exp_f32_e32 v103, v103
	v_add_f32_e32 v79, v102, v79
	v_add_f32_e32 v78, v118, v78
	ds_read_b64_tr_b16 v[70:71], v0 offset:8192
	ds_read_b64_tr_b16 v[72:73], v0 offset:10240
	s_waitcnt lgkmcnt(4)
	v_mfma_f32_32x32x16_bf16 v[18:33], v[90:93], v[66:69], v[18:33]
	v_exp_f32_e32 v120, v120
	v_exp_f32_e32 v104, v104
	v_add_f32_e32 v79, v103, v79
	v_add_f32_e32 v78, v119, v78
	s_add_i32 m0, s10, 0x2000
	ds_read_b64_tr_b16 v[66:67], v0 offset:8704
	ds_read_b64_tr_b16 v[68:69], v0 offset:10752
	global_load_lds_dwordx4 v170, vcc
	s_waitcnt lgkmcnt(4)
	v_mfma_f32_32x32x16_bf16 v[2:17], v[90:93], v[74:77], v[2:17]
	v_exp_f32_e32 v121, v121
	v_exp_f32_e32 v105, v105
	v_add_f32_e32 v79, v104, v79
	v_add_f32_e32 v78, v120, v78
	ds_read_b64_tr_b16 v[74:75], v0 offset:9216
	ds_read_b64_tr_b16 v[76:77], v0 offset:11264
	s_waitcnt lgkmcnt(4)
	v_mfma_f32_32x32x16_bf16 v[50:65], v[86:89], v[70:73], v[50:65]
	v_exp_f32_e32 v122, v122
	v_exp_f32_e32 v106, v106
	v_add_f32_e32 v79, v105, v79
	v_add_f32_e32 v78, v121, v78
	ds_read_b64_tr_b16 v[70:71], v0 offset:9728
	ds_read_b64_tr_b16 v[72:73], v0 offset:11776
	s_waitcnt lgkmcnt(4)
	v_mfma_f32_32x32x16_bf16 v[34:49], v[86:89], v[66:69], v[34:49]
	v_exp_f32_e32 v123, v123
	v_exp_f32_e32 v107, v107
	v_add_f32_e32 v66, v106, v79
	v_add_f32_e32 v67, v122, v78
	ds_read_b64_tr_b16 v[78:79], v0 offset:12288
	ds_read_b64_tr_b16 v[80:81], v0 offset:14336
	s_waitcnt lgkmcnt(4)
	v_mfma_f32_32x32x16_bf16 v[18:33], v[86:89], v[74:77], v[18:33]
	v_exp_f32_e32 v124, v124
	v_exp_f32_e32 v108, v108
	v_add_f32_e32 v66, v107, v66
	v_add_f32_e32 v67, v123, v67
	ds_read_b64_tr_b16 v[74:75], v0 offset:12800
	ds_read_b64_tr_b16 v[76:77], v0 offset:14848
	s_waitcnt lgkmcnt(4)
	v_mfma_f32_32x32x16_bf16 v[2:17], v[86:89], v[70:73], v[2:17]
	v_exp_f32_e32 v125, v125
	v_exp_f32_e32 v109, v109
	v_add_f32_e32 v90, v108, v66
	v_add_f32_e32 v91, v124, v67
	v_add_u32_e32 v70, s12, v224
	ds_read_b64_tr_b16 v[86:87], v0 offset:13312
	ds_read_b64_tr_b16 v[88:89], v0 offset:15360
	ds_read_b128 v[66:69], v70
	ds_read_b128 v[70:73], v70 offset:8192
	s_waitcnt lgkmcnt(6)
	v_mfma_f32_32x32x16_bf16 v[50:65], v[82:85], v[78:81], v[50:65]
	v_exp_f32_e32 v126, v126
	v_exp_f32_e32 v110, v110
	v_add_f32_e32 v90, v109, v90
	v_add_f32_e32 v91, v125, v91
	ds_read_b64_tr_b16 v[78:79], v0 offset:13824
	ds_read_b64_tr_b16 v[80:81], v0 offset:15872
	v_add_u32_e32 v0, s12, v225
	ds_read_b128 v[162:165], v0
	ds_read_b128 v[166:169], v0 offset:8192
	s_waitcnt lgkmcnt(8)
	v_mfma_f32_32x32x16_bf16 v[34:49], v[82:85], v[74:77], v[34:49]
	v_exp_f32_e32 v127, v127
	v_exp_f32_e32 v111, v111
	v_add_f32_e32 v0, v110, v90
	v_add_f32_e32 v74, v126, v91
	s_waitcnt lgkmcnt(6)
	v_mfma_f32_32x32x16_bf16 v[18:33], v[82:85], v[86:89], v[18:33]
	v_exp_f32_e32 v128, v128
	v_exp_f32_e32 v112, v112
	v_add_f32_e32 v0, v111, v0
	v_add_f32_e32 v74, v127, v74
	s_waitcnt lgkmcnt(2)
	v_mfma_f32_32x32x16_bf16 v[2:17], v[82:85], v[78:81], v[2:17]
	v_exp_f32_e32 v129, v129
	v_exp_f32_e32 v113, v113
	v_add_f32_e32 v0, v112, v0
	v_add_f32_e32 v74, v128, v74
	s_nop 0
	v_add_f32_e32 v74, v129, v74
	v_add_f32_e32 v0, v113, v0
	v_add_f32_e32 v0, v74, v0
	v_mov_b32_e32 v226, v0
	s_nop 1
	v_permlane32_swap_b32_e32 v0, v226
	s_mov_b64 s[10:11], -1
	s_waitcnt lgkmcnt(0)
; template <int DK, bool NOMAX> ...
;     ...
;   for (int d0 = 0; d0 < NS; ++d0) {
;     if (d0 == 0) { c0 = __builtin_amdgcn_mfma_f32_32x32x16_bf16(kf[0][0], qr[0], f32x16{}, 0, 0, 0); c1 = __builtin_amdgcn_mfma_f32_32x32x16_bf16(kf[0][1], qr[0], f32x16{}, 0, 0, 0); }
;     else { c0 = __builtin_amdgcn_mfma_f32_32x32x16_bf16(kf[d0 & 1][0], qr[d0], c0, 0, 0, 0); c1 = __builtin_amdgcn_mfma_f32_32x32x16_bf16(kf[d0 & 1][1], qr[d0], c1, 0, 0, 0); }
;     if (d0 + 2 < NS) KRD_(d0 & 1, d0 + 2);
;     if constexpr (NOMAX) { }
;     else {
; #pragma unroll
;     for (int r = d0 * RPS; r < (d0 + 1) * RPS; ++r) { p1[r] = __builtin_amdgcn_exp2f(p1[r]); psa += p0[r]; }
;     if (d0 > 0) {
; #pragma unroll
;       for (int r = (d0 - 1) * RPS; r < d0 * RPS; ++r) psb += p1[r]; } }
;     if constexpr (NOMAX) {
;       if (d0 == NS / 4 - 1) { PK4R(p0, 0, pa[0]); PIN(pa[0]); }
;       if (d0 == NS / 2 - 1) { PK4R(p0, 8, pa[1]); PIN(pa[1]); }
;       if (d0 == 3 * NS / 4 - 1) { PK4R(p1, 0, pa[2]); PIN(pa[2]); }
;       if (d0 == NS - 1) { PK4R(p1, 8, pa[3]); PIN(pa[3]); }
;     } else {
;     if (d0 == NS / 2 - 1) { PK4R(p0, 0, pa[0]); PIN(pa[0]); }
;     if (d0 == NS / 2) { PK4R(p0, 8, pa[1]); PIN(pa[1]); }
;     if (d0 == NS - 1) { PK4R(p1, 0, pa[2]); PIN(pa[2]); }
;     }
;     if (d0 == NS - 1) {
;       vl[0] = vtr(vp + v_rd_off(0, 0, 0)); vh[0] = vtr(vp + v_rd_off(0, 0, 1)); vl[1] = vtr(vp + v_rd_off(1, 0, 0)); vh[1] = vtr(vp + v_rd_off(1, 0, 1)); }
;     PIN(p1); PIN(psa); PIN(psb);
;     SBAR();
;   }
; template <int DK, bool NOMAX> ...
;     ...
;   for (int i = 0; i < 16; ++i) {
;     if (i + 2 < 16) VRD_((i + 2) % 3, i + 2);
;     if (i == 1) { if (dk) __builtin_amdgcn_global_load_lds((const unsigned*)gk0, lk, 16, 0, 0); }
;     if (i == 3) { if constexpr (DK == 128) { if (dk) __builtin_amdgcn_global_load_lds((const unsigned*)gk1, (lds_up)((lds_cp)lk + 8192), 16, 0, 0); } }
;     if (i == 5) { if (dv) __builtin_amdgcn_global_load_lds((const unsigned*)gv0, lv, 16, 0, 0); }
;     if (i == 7) { if (dv) __builtin_amdgcn_global_load_lds((const unsigned*)gv1, (lds_up)((lds_cp)lv + 8192), 16, 0, 0); }
;     if (i == 12 || i == 13) { const int cb_ = ((i - 12) * 16 + hi * 8) * 2;
;       if constexpr (DK == 128) { kf[i - 12][0] = *reinterpret_cast<const bf16x8*>(Kn + KSWZ128(r32, cb_)); kf[i - 12][1] = *reinterpret_cast<const bf16x8*>(Kn + KSWZ128(32 + r32, cb_)); }
.LBB0_408:
.LBB0_410:
	v_add_u32_e32 v227, s17, v204
	v_mfma_f32_32x32x16_bf16 v[82:97], v[66:69], v[158:161], 0
	v_add_u32_e32 v232, s12, v218
	ds_read_b128 v[228:231], v232
	ds_read_b128 v[232:235], v232 offset:8192
	v_mfma_f32_32x32x16_bf16 v[66:81], v[70:73], v[158:161], 0
	v_mfma_f32_32x32x16_bf16 v[82:97], v[162:165], v[154:157], v[82:97]
	v_add_u32_e32 v162, s12, v219
	v_mfma_f32_32x32x16_bf16 v[66:81], v[166:169], v[154:157], v[66:81]
	ds_read_b128 v[166:169], v162
	ds_read_b128 v[236:239], v162 offset:8192
	v_cvt_pk_bf16_f32 v162, v114, v115
	v_cvt_pk_bf16_f32 v163, v116, v117
	v_cvt_pk_bf16_f32 v164, v118, v119
	v_cvt_pk_bf16_f32 v165, v120, v121
	s_nop 0
	v_permlane32_swap_b32_e32 v162, v164
	v_permlane32_swap_b32_e32 v163, v165
	s_waitcnt lgkmcnt(3)
	v_mfma_f32_32x32x16_bf16 v[82:97], v[228:231], v[150:153], v[82:97]
	v_add_u32_e32 v118, s12, v220
	ds_read_b128 v[114:117], v118
	ds_read_b128 v[118:121], v118 offset:8192
	s_waitcnt lgkmcnt(4)
	v_mfma_f32_32x32x16_bf16 v[66:81], v[232:235], v[150:153], v[66:81]
	s_waitcnt lgkmcnt(3)
	v_mfma_f32_32x32x16_bf16 v[82:97], v[166:169], v[146:149], v[82:97]
	v_add_u32_e32 v228, s12, v221
	ds_read_b128 v[166:169], v228
	ds_read_b128 v[228:231], v228 offset:8192
	v_cvt_pk_bf16_f32 v122, v122, v123
	v_cvt_pk_bf16_f32 v123, v124, v125
	v_cvt_pk_bf16_f32 v124, v126, v127
	v_cvt_pk_bf16_f32 v125, v128, v129
	s_waitcnt lgkmcnt(4)
	v_mfma_f32_32x32x16_bf16 v[66:81], v[236:239], v[146:149], v[66:81]
	v_permlane32_swap_b32_e32 v122, v124
	v_permlane32_swap_b32_e32 v123, v125
	s_waitcnt lgkmcnt(3)
	v_mfma_f32_32x32x16_bf16 v[82:97], v[114:117], v[142:145], v[82:97]
	s_waitcnt lgkmcnt(2)
	v_mfma_f32_32x32x16_bf16 v[66:81], v[118:121], v[142:145], v[66:81]
	v_add_u32_e32 v118, s12, v222
	ds_read_b128 v[114:117], v118
	ds_read_b128 v[126:129], v118 offset:8192
	s_waitcnt lgkmcnt(3)
	v_mfma_f32_32x32x16_bf16 v[82:97], v[166:169], v[138:141], v[82:97]
	v_add_u32_e32 v118, s12, v223
	s_waitcnt lgkmcnt(2)
	v_mfma_f32_32x32x16_bf16 v[66:81], v[228:231], v[138:141], v[66:81]
	ds_read_b128 v[166:169], v118
	ds_read_b128 v[228:231], v118 offset:8192
	v_cvt_pk_bf16_f32 v118, v98, v99
	v_cvt_pk_bf16_f32 v119, v100, v101
	v_cvt_pk_bf16_f32 v120, v102, v103
	v_cvt_pk_bf16_f32 v121, v104, v105
	s_nop 0
	v_permlane32_swap_b32_e32 v118, v120
	v_permlane32_swap_b32_e32 v119, v121
	s_waitcnt lgkmcnt(3)
	v_mfma_f32_32x32x16_bf16 v[82:97], v[114:117], v[130:133], v[82:97]
	s_waitcnt lgkmcnt(2)
	v_mfma_f32_32x32x16_bf16 v[66:81], v[126:129], v[130:133], v[66:81]
	v_cvt_pk_bf16_f32 v114, v106, v107
	v_cvt_pk_bf16_f32 v115, v108, v109
	v_cvt_pk_bf16_f32 v116, v110, v111
	v_cvt_pk_bf16_f32 v117, v112, v113
	s_waitcnt lgkmcnt(1)
	v_mfma_f32_32x32x16_bf16 v[82:97], v[166:169], v[134:137], v[82:97]
	v_permlane32_swap_b32_e32 v114, v116
	v_permlane32_swap_b32_e32 v115, v117
	s_cmpk_gt_i32 s15, 0x7c
	s_cbranch_scc1 .Lmy_mb0_b1_2
	s_waitcnt vmcnt(4) lgkmcnt(0)
	s_barrier
.Lmy_mbj_b1_2:
	ds_read_b64_tr_b16 v[166:167], v227
	ds_read_b64_tr_b16 v[168:169], v227 offset:2048
	ds_read_b64_tr_b16 v[126:127], v227 offset:512
	ds_read_b64_tr_b16 v[128:129], v227 offset:2560
	s_waitcnt lgkmcnt(4)
	v_mfma_f32_32x32x16_bf16 v[66:81], v[228:231], v[134:137], v[66:81]
	s_cmpk_lt_u32 s15, 0x7c
	s_cselect_b64 s[12:13], -1, 0
	s_cmpk_gt_u32 s15, 0x7b
	s_cselect_b64 s[10:11], -1, 0
	ds_read_b64_tr_b16 v[102:103], v227 offset:1024
	ds_read_b64_tr_b16 v[104:105], v227 offset:3072
	s_waitcnt lgkmcnt(4)
	v_mfma_f32_32x32x16_bf16 v[50:65], v[162:165], v[166:169], v[50:65]
	v_exp_f32_e32 v82, v82
	s_nop 2
	v_exp_f32_e32 v66, v66
	ds_read_b64_tr_b16 v[98:99], v227 offset:1536
	ds_read_b64_tr_b16 v[100:101], v227 offset:3584
	s_and_b64 vcc, exec, s[10:11]
	s_cbranch_vccnz .LBB0_412
	s_add_u32 vcc_lo, s0, s64
	s_addc_u32 vcc_hi, s1, s65
	s_add_i32 m0, s2, s38
	s_nop 0
	global_load_lds_dwordx4 v182, vcc

; template <int DK, bool NOMAX> ...
;     ...
;   for (int i = 0; i < 16; ++i) {
;     if (i + 2 < 16) VRD_((i + 2) % 3, i + 2);
;     if (i == 1) { if (dk) __builtin_amdgcn_global_load_lds((const unsigned*)gk0, lk, 16, 0, 0); }
;     if (i == 3) { if constexpr (DK == 128) { if (dk) __builtin_amdgcn_global_load_lds((const unsigned*)gk1, (lds_up)((lds_cp)lk + 8192), 16, 0, 0); } }
;     if (i == 5) { if (dv) __builtin_amdgcn_global_load_lds((const unsigned*)gv0, lv, 16, 0, 0); }
;     if (i == 7) { if (dv) __builtin_amdgcn_global_load_lds((const unsigned*)gv1, (lds_up)((lds_cp)lv + 8192), 16, 0, 0); }
;     if (i == 12 || i == 13) { const int cb_ = ((i - 12) * 16 + hi * 8) * 2;
;       if constexpr (DK == 128) { kf[i - 12][0] = *reinterpret_cast<const bf16x8*>(Kn + KSWZ128(r32, cb_)); kf[i - 12][1] = *reinterpret_cast<const bf16x8*>(Kn + KSWZ128(32 + r32, cb_)); }
;       else { kf[i - 12][0] = *reinterpret_cast<const bf16x8*>(Kn + KSWZ64(r32, cb_)); kf[i - 12][1] = *reinterpret_cast<const bf16x8*>(Kn + KSWZ64(32 + r32, cb_)); } }
;     SBAR();
;     o[i & 3] = __builtin_amdgcn_mfma_f32_32x32x16_bf16(pa[i >> 2], VFR_(i % 3), o[i & 3], 0, 0, 0);
;     if constexpr (NOMAX) { c0[i] = __builtin_amdgcn_exp2f(c0[i]); c1[i] = __builtin_amdgcn_exp2f(c1[i]); if (i > 0) { psa += c0[i - 1]; psb += c1[i - 1]; } PIN(c0); PIN(c1); PIN(psa); PIN(psb); }
;     else {
;     if (i == 0) { ma = max3f(c0[0], c0[1], c1[0]); mb = max3f(c0[2], c0[3], c1[1]); ma = max3f(ma, c1[2], c1[3]); }
;     if (i >= 1 && i <= 3) { const int r = 4 * i; ma = max3f(ma, c0[r], c0[r + 1]); mb = max3f(mb, c0[r + 2], c0[r + 3]); ma = max3f(ma, c1[r], c1[r + 1]); mb = max3f(mb, c1[r + 2], c1[r + 3]); }
;     if (i == 4) { float pmax = fmaxf(ma, mb);
;       { auto rr = __builtin_amdgcn_permlane32_swap(__float_as_uint(pmax), __float_as_uint(pmax), false, false);
;         pmax = fmaxf(__uint_as_float(rr[0]), __uint_as_float(rr[1])); }
;       pmax += cb;
;       const bool keep = __all(pmax - m_reg <= THR2);
;       const float mn = keep ? m_reg : fmaxf(m_reg, pmax);
;       alpha = __builtin_amdgcn_exp2f(m_reg - mn); m_reg = mn; mnC = cb - mn; }
;     if (i >= 5 && i <= 8) { const int r = 4 * (i - 5);
; #pragma unroll
;       for (int q = 0; q < 4; ++q) { c0[r + q] += mnC; c1[r + q] += mnC; } }
;     if (i >= 9) { const int r0 = (i - 9) * 2 + (i > 14 ? 1 : 0), n = i >= 14 ? 3 : 2;
; #pragma unroll
.LBB0_414:
	s_add_i32 s12, s18, 0x4000
	s_and_b32 s12, s12, 0xc000
	s_add_i32 s12, s12, 0
	s_waitcnt lgkmcnt(4)
	v_mfma_f32_32x32x16_bf16 v[2:17], v[162:165], v[98:101], v[2:17]
	v_exp_f32_e32 v85, v85
	v_exp_f32_e32 v69, v69
	v_add_f32_e32 v111, v68, v111
	v_add_f32_e32 v110, v84, v110
	ds_read_b64_tr_b16 v[98:99], v227 offset:5120
	ds_read_b64_tr_b16 v[100:101], v227 offset:7168
	s_waitcnt lgkmcnt(4)
	v_mfma_f32_32x32x16_bf16 v[50:65], v[122:125], v[106:109], v[50:65]
	v_exp_f32_e32 v86, v86
	v_exp_f32_e32 v70, v70
	v_add_f32_e32 v111, v69, v111
	v_add_f32_e32 v110, v85, v110
	s_add_u32 vcc_lo, s0, s24
	s_addc_u32 vcc_hi, s1, s25
	s_add_i32 s13, s3, s14
	s_mov_b32 m0, s13
	ds_read_b64_tr_b16 v[106:107], v227 offset:5632
	ds_read_b64_tr_b16 v[108:109], v227 offset:7680
	global_load_lds_dwordx4 v172, vcc
	s_waitcnt lgkmcnt(4)
	v_mfma_f32_32x32x16_bf16 v[34:49], v[122:125], v[102:105], v[34:49]
	v_exp_f32_e32 v87, v87
	v_exp_f32_e32 v71, v71
	v_add_f32_e32 v111, v70, v111
	v_add_f32_e32 v110, v86, v110
	ds_read_b64_tr_b16 v[102:103], v227 offset:8192
	ds_read_b64_tr_b16 v[104:105], v227 offset:10240
	s_waitcnt lgkmcnt(4)
	v_mfma_f32_32x32x16_bf16 v[18:33], v[122:125], v[98:101], v[18:33]
	v_exp_f32_e32 v88, v88
	v_exp_f32_e32 v72, v72
	v_add_f32_e32 v111, v71, v111
	v_add_f32_e32 v110, v87, v110
	s_add_i32 m0, s13, 0x2000
	ds_read_b64_tr_b16 v[98:99], v227 offset:8704
	ds_read_b64_tr_b16 v[100:101], v227 offset:10752
	global_load_lds_dwordx4 v170, vcc
	s_waitcnt lgkmcnt(4)
	v_mfma_f32_32x32x16_bf16 v[2:17], v[122:125], v[106:109], v[2:17]
	v_exp_f32_e32 v89, v89
	v_exp_f32_e32 v73, v73
	v_add_f32_e32 v111, v72, v111
	v_add_f32_e32 v110, v88, v110
	ds_read_b64_tr_b16 v[106:107], v227 offset:9216
	ds_read_b64_tr_b16 v[108:109], v227 offset:11264
	s_waitcnt lgkmcnt(4)
	v_mfma_f32_32x32x16_bf16 v[50:65], v[118:121], v[102:105], v[50:65]
	v_exp_f32_e32 v90, v90
	v_exp_f32_e32 v74, v74
	v_add_f32_e32 v111, v73, v111
	v_add_f32_e32 v110, v89, v110
	ds_read_b64_tr_b16 v[102:103], v227 offset:9728
	ds_read_b64_tr_b16 v[104:105], v227 offset:11776
	s_waitcnt lgkmcnt(4)
	v_mfma_f32_32x32x16_bf16 v[34:49], v[118:121], v[98:101], v[34:49]
	v_exp_f32_e32 v91, v91
	v_exp_f32_e32 v75, v75
	v_add_f32_e32 v98, v74, v111
	v_add_f32_e32 v99, v90, v110
	ds_read_b64_tr_b16 v[110:111], v227 offset:12288
	ds_read_b64_tr_b16 v[112:113], v227 offset:14336
	s_waitcnt lgkmcnt(4)
	v_mfma_f32_32x32x16_bf16 v[18:33], v[118:121], v[106:109], v[18:33]
	v_exp_f32_e32 v92, v92
	v_exp_f32_e32 v76, v76
	v_add_f32_e32 v98, v75, v98
	v_add_f32_e32 v99, v91, v99
	ds_read_b64_tr_b16 v[106:107], v227 offset:12800
	ds_read_b64_tr_b16 v[108:109], v227 offset:14848
	s_waitcnt lgkmcnt(4)
	v_mfma_f32_32x32x16_bf16 v[2:17], v[118:121], v[102:105], v[2:17]
	v_exp_f32_e32 v93, v93
	v_exp_f32_e32 v77, v77
	v_add_f32_e32 v122, v76, v98
	v_add_f32_e32 v123, v92, v99
	v_add_u32_e32 v98, s12, v224
	ds_read_b64_tr_b16 v[118:119], v227 offset:13312
	ds_read_b64_tr_b16 v[120:121], v227 offset:15360
	ds_read_b128 v[102:105], v98
	ds_read_b128 v[98:101], v98 offset:8192
	s_waitcnt lgkmcnt(6)
	v_mfma_f32_32x32x16_bf16 v[50:65], v[114:117], v[110:113], v[50:65]
	v_exp_f32_e32 v94, v94
	v_exp_f32_e32 v78, v78
	v_add_f32_e32 v122, v77, v122
	v_add_f32_e32 v123, v93, v123
	v_add_u32_e32 v124, s12, v225
	ds_read_b64_tr_b16 v[110:111], v227 offset:13824
	ds_read_b64_tr_b16 v[112:113], v227 offset:15872
	ds_read_b128 v[166:169], v124
	ds_read_b128 v[162:165], v124 offset:8192
	s_waitcnt lgkmcnt(8)
	v_mfma_f32_32x32x16_bf16 v[34:49], v[114:117], v[106:109], v[34:49]
	v_exp_f32_e32 v95, v95
	v_exp_f32_e32 v79, v79
	v_add_f32_e32 v106, v78, v122
	v_add_f32_e32 v107, v94, v123
	s_waitcnt lgkmcnt(6)
	v_mfma_f32_32x32x16_bf16 v[18:33], v[114:117], v[118:121], v[18:33]
	v_exp_f32_e32 v96, v96
	v_exp_f32_e32 v80, v80
	v_add_f32_e32 v106, v79, v106
	v_add_f32_e32 v107, v95, v107
	s_waitcnt lgkmcnt(2)
	v_mfma_f32_32x32x16_bf16 v[2:17], v[114:117], v[110:113], v[2:17]
	v_exp_f32_e32 v97, v97
	v_exp_f32_e32 v81, v81
	v_add_f32_e32 v106, v80, v106
	v_add_f32_e32 v107, v96, v107
	s_nop 0
	v_add_f32_e32 v107, v97, v107
	v_add_f32_e32 v106, v81, v106
	v_add_f32_e32 v106, v107, v106
	v_mov_b32_e32 v107, v106
	s_nop 1
	v_permlane32_swap_b32_e32 v106, v107
	s_mov_b64 s[12:13], -1
	s_waitcnt lgkmcnt(0)
.LBB0_416:
.LBB0_418:
	v_add_f32_e32 v0, v0, v226
	s_add_i32 s15, s15, 2
	v_add_f32_e32 v0, v203, v0
	v_add_f32_e32 v106, v106, v107
	s_add_u32 s0, s0, 0x10000
	s_addc_u32 s1, s1, 0
	s_andn2_b64 vcc, exec, s[8:9]
	v_add_f32_e32 v203, v0, v106
	s_cbranch_vccz .LBB0_420
	s_mov_b32 s18, s19
	s_mov_b32 s8, s16
	s_mov_b32 s16, s17
	s_branch .LBB0_402

; template <int DK, bool NOMAX> ...
;     ...
;   for (int d0 = 0; d0 < NS; ++d0) {
;     if (d0 == 0) { c0 = __builtin_amdgcn_mfma_f32_32x32x16_bf16(kf[0][0], qr[0], f32x16{}, 0, 0, 0); c1 = __builtin_amdgcn_mfma_f32_32x32x16_bf16(kf[0][1], qr[0], f32x16{}, 0, 0, 0); }
;     else { c0 = __builtin_amdgcn_mfma_f32_32x32x16_bf16(kf[d0 & 1][0], qr[d0], c0, 0, 0, 0); c1 = __builtin_amdgcn_mfma_f32_32x32x16_bf16(kf[d0 & 1][1], qr[d0], c1, 0, 0, 0); }
;     if (d0 + 2 < NS) KRD_(d0 & 1, d0 + 2);
;     if constexpr (NOMAX) { }
;     else {
; #pragma unroll
;     for (int r = d0 * RPS; r < (d0 + 1) * RPS; ++r) { p1[r] = __builtin_amdgcn_exp2f(p1[r]); psa += p0[r]; }
;     if (d0 > 0) {
; #pragma unroll
;       for (int r = (d0 - 1) * RPS; r < d0 * RPS; ++r) psb += p1[r]; } }
;     if constexpr (NOMAX) {
;       if (d0 == NS / 4 - 1) { PK4R(p0, 0, pa[0]); PIN(pa[0]); }
;       if (d0 == NS / 2 - 1) { PK4R(p0, 8, pa[1]); PIN(pa[1]); }
;       if (d0 == 3 * NS / 4 - 1) { PK4R(p1, 0, pa[2]); PIN(pa[2]); }
;       if (d0 == NS - 1) { PK4R(p1, 8, pa[3]); PIN(pa[3]); }
;     } else {
;     if (d0 == NS / 2 - 1) { PK4R(p0, 0, pa[0]); PIN(pa[0]); }
;     if (d0 == NS / 2) { PK4R(p0, 8, pa[1]); PIN(pa[1]); }
;     if (d0 == NS - 1) { PK4R(p1, 0, pa[2]); PIN(pa[2]); }
;     }
;     if (d0 == NS - 1) {
;       vl[0] = vtr(vp + v_rd_off(0, 0, 0)); vh[0] = vtr(vp + v_rd_off(0, 0, 1)); vl[1] = vtr(vp + v_rd_off(1, 0, 0)); vh[1] = vtr(vp + v_rd_off(1, 0, 1)); }
;     PIN(p1); PIN(psa); PIN(psb);
;     SBAR();
;   }
; template <int DK, bool NOMAX> ...
;     ...
;   for (int i = 0; i < 16; ++i) {
;     if (i + 2 < 16) VRD_((i + 2) % 3, i + 2);
;     if (i == 1) { if (dk) __builtin_amdgcn_global_load_lds((const unsigned*)gk0, lk, 16, 0, 0); }
;     if (i == 3) { if constexpr (DK == 128) { if (dk) __builtin_amdgcn_global_load_lds((const unsigned*)gk1, (lds_up)((lds_cp)lk + 8192), 16, 0, 0); } }
;     if (i == 5) { if (dv) __builtin_amdgcn_global_load_lds((const unsigned*)gv0, lv, 16, 0, 0); }
;     if (i == 7) { if (dv) __builtin_amdgcn_global_load_lds((const unsigned*)gv1, (lds_up)((lds_cp)lv + 8192), 16, 0, 0); }
;     if (i == 12 || i == 13) { const int cb_ = ((i - 12) * 16 + hi * 8) * 2;
;       if constexpr (DK == 128) { kf[i - 12][0] = *reinterpret_cast<const bf16x8*>(Kn + KSWZ128(r32, cb_)); kf[i - 12][1] = *reinterpret_cast<const bf16x8*>(Kn + KSWZ128(32 + r32, cb_)); }
.LBB0_420:
	v_add3_u32 v0, 0, v217, v205
	ds_read_b128 v[170:173], v0 offset:49152
	ds_read_b128 v[180:183], v216 offset:57344
	v_mov_b32_e32 v0, v1
	v_mov_b32_e32 v188, v1
	v_mfma_f32_32x32x16_bf16 v[114:129], v[102:105], v[158:161], 0
	v_mfma_f32_32x32x16_bf16 v[98:113], v[98:101], v[158:161], 0
	v_mfma_f32_32x32x16_bf16 v[98:113], v[162:165], v[154:157], v[98:113]
	v_add3_u32 v162, 0, v215, v205
	v_mfma_f32_32x32x16_bf16 v[114:129], v[166:169], v[154:157], v[114:129]
	ds_read_b128 v[166:169], v162 offset:49152
	ds_read_b128 v[184:187], v214 offset:57344
	v_cvt_pk_bf16_f32 v162, v82, v83
	v_cvt_pk_bf16_f32 v163, v84, v85
	v_cvt_pk_bf16_f32 v164, v86, v87
	v_cvt_pk_bf16_f32 v165, v88, v89
	s_nop 0
	v_permlane32_swap_b32_e32 v162, v164
	v_permlane32_swap_b32_e32 v163, v165
	v_add3_u32 v82, 0, v213, v205
	ds_read_b128 v[82:85], v82 offset:49152
	ds_read_b128 v[86:89], v212 offset:57344
	s_waitcnt lgkmcnt(5)
	v_mfma_f32_32x32x16_bf16 v[114:129], v[170:173], v[150:153], v[114:129]
	s_waitcnt lgkmcnt(4)
	v_mfma_f32_32x32x16_bf16 v[98:113], v[180:183], v[150:153], v[98:113]
	s_waitcnt lgkmcnt(3)
	v_mfma_f32_32x32x16_bf16 v[114:129], v[166:169], v[146:149], v[114:129]
	v_add3_u32 v166, 0, v211, v205
	ds_read_b128 v[166:169], v166 offset:49152
	ds_read_b128 v[170:173], v210 offset:57344
	v_cvt_pk_bf16_f32 v90, v90, v91
	v_cvt_pk_bf16_f32 v91, v92, v93
	v_cvt_pk_bf16_f32 v92, v94, v95
	v_cvt_pk_bf16_f32 v93, v96, v97
	s_nop 0
	v_permlane32_swap_b32_e32 v90, v92
	v_permlane32_swap_b32_e32 v91, v93
	s_waitcnt lgkmcnt(4)
	v_mfma_f32_32x32x16_bf16 v[98:113], v[184:187], v[146:149], v[98:113]
	s_waitcnt lgkmcnt(3)
	v_mfma_f32_32x32x16_bf16 v[114:129], v[82:85], v[142:145], v[114:129]
	v_add3_u32 v82, 0, v209, v205
	ds_read_b128 v[82:85], v82 offset:49152
	ds_read_b128 v[94:97], v208 offset:57344
	s_waitcnt lgkmcnt(4)
	v_mfma_f32_32x32x16_bf16 v[98:113], v[86:89], v[142:145], v[98:113]
	v_add3_u32 v86, 0, v207, v205
	s_waitcnt lgkmcnt(3)
	v_mfma_f32_32x32x16_bf16 v[114:129], v[166:169], v[138:141], v[114:129]
	s_waitcnt lgkmcnt(2)
	v_mfma_f32_32x32x16_bf16 v[98:113], v[170:173], v[138:141], v[98:113]
	ds_read_b128 v[166:169], v86 offset:49152
	ds_read_b128 v[170:173], v206 offset:57344
	v_cvt_pk_bf16_f32 v86, v66, v67
	v_cvt_pk_bf16_f32 v87, v68, v69
	v_cvt_pk_bf16_f32 v88, v70, v71
	v_cvt_pk_bf16_f32 v89, v72, v73
	s_nop 0
	v_permlane32_swap_b32_e32 v86, v88
	v_permlane32_swap_b32_e32 v87, v89
	s_waitcnt lgkmcnt(3)
	v_mfma_f32_32x32x16_bf16 v[114:129], v[82:85], v[130:133], v[114:129]
	s_waitcnt lgkmcnt(2)
	v_mfma_f32_32x32x16_bf16 v[98:113], v[94:97], v[130:133], v[98:113]
	v_cvt_pk_bf16_f32 v82, v74, v75
	v_cvt_pk_bf16_f32 v83, v76, v77
	v_cvt_pk_bf16_f32 v84, v78, v79
	v_cvt_pk_bf16_f32 v85, v80, v81
	s_waitcnt lgkmcnt(1)
	v_mfma_f32_32x32x16_bf16 v[114:129], v[166:169], v[134:137], v[114:129]
	v_permlane32_swap_b32_e32 v82, v84
	v_permlane32_swap_b32_e32 v83, v85
	s_waitcnt vmcnt(0) lgkmcnt(0)
	s_barrier
	ds_read_b64_tr_b16 v[94:95], v204
	ds_read_b64_tr_b16 v[96:97], v204 offset:2048
	ds_read_b64_tr_b16 v[166:167], v204 offset:512
	ds_read_b64_tr_b16 v[168:169], v204 offset:2560
	s_waitcnt lgkmcnt(4)
	v_mfma_f32_32x32x16_bf16 v[98:113], v[170:173], v[134:137], v[98:113]
	ds_read_b64_tr_b16 v[66:67], v204 offset:1024
	ds_read_b64_tr_b16 v[68:69], v204 offset:3072
	s_waitcnt lgkmcnt(4)
	v_mfma_f32_32x32x16_bf16 v[50:65], v[162:165], v[94:97], v[50:65]
	s_nop 0
	v_exp_f32_e32 v114, v114
	s_nop 5
	v_exp_f32_e32 v98, v98
	v_mov_b32_e32 v0, v1
	v_mov_b32_e32 v74, v1
	ds_read_b64_tr_b16 v[70:71], v204 offset:1536
	ds_read_b64_tr_b16 v[72:73], v204 offset:3584
	s_waitcnt lgkmcnt(4)
	v_mfma_f32_32x32x16_bf16 v[34:49], v[162:165], v[166:169], v[34:49]
	v_exp_f32_e32 v115, v115
	v_exp_f32_e32 v99, v99
	v_add_f32_e32 v78, v98, v74
	v_add_f32_e32 v0, v114, v0
	ds_read_b64_tr_b16 v[74:75], v204 offset:4096
	ds_read_b64_tr_b16 v[76:77], v204 offset:6144
	s_waitcnt lgkmcnt(4)
	v_mfma_f32_32x32x16_bf16 v[18:33], v[162:165], v[66:69], v[18:33]
	v_exp_f32_e32 v116, v116
	v_exp_f32_e32 v100, v100
	v_add_f32_e32 v78, v99, v78
	v_add_f32_e32 v0, v115, v0
	ds_read_b64_tr_b16 v[66:67], v204 offset:4608
	ds_read_b64_tr_b16 v[68:69], v204 offset:6656
	s_waitcnt lgkmcnt(4)
	v_mfma_f32_32x32x16_bf16 v[2:17], v[162:165], v[70:73], v[2:17]
	v_exp_f32_e32 v117, v117
	v_exp_f32_e32 v101, v101
	v_add_f32_e32 v78, v100, v78
	v_add_f32_e32 v0, v116, v0
	ds_read_b64_tr_b16 v[70:71], v204 offset:5120
	ds_read_b64_tr_b16 v[72:73], v204 offset:7168
	s_waitcnt lgkmcnt(4)
	v_mfma_f32_32x32x16_bf16 v[50:65], v[90:93], v[74:77], v[50:65]
	v_exp_f32_e32 v118, v118
	v_exp_f32_e32 v102, v102
	v_add_f32_e32 v78, v101, v78
	v_add_f32_e32 v0, v117, v0
	ds_read_b64_tr_b16 v[74:75], v204 offset:5632
	ds_read_b64_tr_b16 v[76:77], v204 offset:7680
	s_waitcnt lgkmcnt(4)
	v_mfma_f32_32x32x16_bf16 v[34:49], v[90:93], v[66:69], v[34:49]
	v_exp_f32_e32 v119, v119
	v_exp_f32_e32 v103, v103
	v_add_f32_e32 v78, v102, v78
	v_add_f32_e32 v0, v118, v0
	ds_read_b64_tr_b16 v[66:67], v204 offset:8192
	ds_read_b64_tr_b16 v[68:69], v204 offset:10240
	s_waitcnt lgkmcnt(4)
	v_mfma_f32_32x32x16_bf16 v[18:33], v[90:93], v[70:73], v[18:33]
	v_exp_f32_e32 v120, v120
	v_exp_f32_e32 v104, v104
	v_add_f32_e32 v78, v103, v78
	v_add_f32_e32 v0, v119, v0
	ds_read_b64_tr_b16 v[70:71], v204 offset:8704
	ds_read_b64_tr_b16 v[72:73], v204 offset:10752
	s_waitcnt lgkmcnt(4)
	v_mfma_f32_32x32x16_bf16 v[2:17], v[90:93], v[74:77], v[2:17]
	v_exp_f32_e32 v121, v121
	v_exp_f32_e32 v105, v105
	v_add_f32_e32 v78, v104, v78
	v_add_f32_e32 v0, v120, v0
	ds_read_b64_tr_b16 v[74:75], v204 offset:9216
	ds_read_b64_tr_b16 v[76:77], v204 offset:11264
	s_waitcnt lgkmcnt(4)
; #define SBAR() __builtin_amdgcn_sched_barrier(0)
; template <int D0> __device__ __forceinline__ void pv_one(f32x16& od, int vb, bf16x8 pa0, bf16x8 pa1, bf16x8 pa2, bf16x8 pa3) {
;   const s16x4 l0 = tr_read<v_rd_off(D0, 0, 0)>(vb), h0 = tr_read<v_rd_off(D0, 0, 1)>(vb), l1 = tr_read<v_rd_off(D0, 1, 0)>(vb), h1 = tr_read<v_rd_off(D0, 1, 1)>(vb);
;   const s16x4 l2 = tr_read<v_rd_off(D0, 2, 0)>(vb), h2 = tr_read<v_rd_off(D0, 2, 1)>(vb), l3 = tr_read<v_rd_off(D0, 3, 0)>(vb), h3 = tr_read<v_rd_off(D0, 3, 1)>(vb);
;   asm volatile("s_waitcnt lgkmcnt(0)" ::: "memory"); SBAR();
;     ...
;   od = __builtin_amdgcn_mfma_f32_32x32x16_bf16(pa0, PK(l0, h0), od, 0, 0, 0);
;   od = __builtin_amdgcn_mfma_f32_32x32x16_bf16(pa1, PK(l1, h1), od, 0, 0, 0);
;   od = __builtin_amdgcn_mfma_f32_32x32x16_bf16(pa2, PK(l2, h2), od, 0, 0, 0);
;   od = __builtin_amdgcn_mfma_f32_32x32x16_bf16(pa3, PK(l3, h3), od, 0, 0, 0);
;     ...
; }
; __device__ __forceinline__ void pv_d0(f32x16* o, int vb, bf16x8 pa0, bf16x8 pa1, bf16x8 pa2, bf16x8 pa3) {
;   pv_one<0>(o[0], vb, pa0, pa1, pa2, pa3); pv_one<1>(o[1], vb, pa0, pa1, pa2, pa3); pv_one<2>(o[2], vb, pa0, pa1, pa2, pa3); pv_one<3>(o[3], vb, pa0, pa1, pa2, pa3);
; template <int DK, int LDK, bool BIAS, bool NOMAX> ...
;     ...
;   STEPT(pB0, pB1, pA0, pA1, alA, alB, NT - 1);
;   if constexpr (NOMAX) { PK4R(pB0, 0, pa[0]); PK4R(pB0, 8, pa[1]); PK4R(pB1, 0, pa[2]); PK4R(pB1, 8, pa[3]); }
;   else finishSM<false>(pB0, pB1, alB, l_reg, pa[0], pa[1], pa[2], pa[3]);
;   SBAR();
;   pv_d0(o, vb0 + sp, pa[0], pa[1], pa[2], pa[3]);
;   l_out = l_reg;
	v_mfma_f32_32x32x16_bf16 v[50:65], v[86:89], v[66:69], v[50:65]
	v_exp_f32_e32 v122, v122
	v_exp_f32_e32 v106, v106
	v_add_f32_e32 v78, v105, v78
	v_add_f32_e32 v0, v121, v0
	ds_read_b64_tr_b16 v[66:67], v204 offset:9728
	ds_read_b64_tr_b16 v[68:69], v204 offset:11776
	s_waitcnt lgkmcnt(4)
	v_mfma_f32_32x32x16_bf16 v[34:49], v[86:89], v[70:73], v[34:49]
	v_exp_f32_e32 v123, v123
	v_exp_f32_e32 v107, v107
	v_add_f32_e32 v78, v106, v78
	v_add_f32_e32 v0, v122, v0
	ds_read_b64_tr_b16 v[70:71], v204 offset:12288
	ds_read_b64_tr_b16 v[72:73], v204 offset:14336
	s_waitcnt lgkmcnt(4)
	v_mfma_f32_32x32x16_bf16 v[18:33], v[86:89], v[74:77], v[18:33]
	v_exp_f32_e32 v124, v124
	v_exp_f32_e32 v108, v108
	v_add_f32_e32 v78, v107, v78
	v_add_f32_e32 v0, v123, v0
	ds_read_b64_tr_b16 v[74:75], v204 offset:12800
	ds_read_b64_tr_b16 v[76:77], v204 offset:14848
	s_waitcnt lgkmcnt(4)
	v_mfma_f32_32x32x16_bf16 v[2:17], v[86:89], v[66:69], v[2:17]
	v_exp_f32_e32 v125, v125
	v_exp_f32_e32 v109, v109
	v_add_f32_e32 v78, v108, v78
	v_add_f32_e32 v0, v124, v0
	ds_read_b64_tr_b16 v[66:67], v204 offset:13312
	ds_read_b64_tr_b16 v[68:69], v204 offset:15360
	s_waitcnt lgkmcnt(4)
	v_mfma_f32_32x32x16_bf16 v[50:65], v[82:85], v[70:73], v[50:65]
	v_exp_f32_e32 v126, v126
	v_exp_f32_e32 v110, v110
	v_add_f32_e32 v78, v109, v78
	v_add_f32_e32 v0, v125, v0
	ds_read_b64_tr_b16 v[70:71], v204 offset:13824
	ds_read_b64_tr_b16 v[72:73], v204 offset:15872
	s_waitcnt lgkmcnt(4)
	v_mfma_f32_32x32x16_bf16 v[34:49], v[82:85], v[74:77], v[34:49]
	v_exp_f32_e32 v127, v127
	v_exp_f32_e32 v111, v111
	v_add_f32_e32 v74, v110, v78
	v_add_f32_e32 v0, v126, v0
	s_waitcnt lgkmcnt(2)
	v_mfma_f32_32x32x16_bf16 v[18:33], v[82:85], v[66:69], v[18:33]
	v_exp_f32_e32 v128, v128
	v_exp_f32_e32 v112, v112
	v_add_f32_e32 v66, v111, v74
	v_add_f32_e32 v0, v127, v0
	s_waitcnt lgkmcnt(0)
	v_mfma_f32_32x32x16_bf16 v[2:17], v[82:85], v[70:73], v[2:17]
	v_exp_f32_e32 v129, v129
	v_exp_f32_e32 v113, v113
	v_add_f32_e32 v67, v112, v66
	v_add_f32_e32 v66, v128, v0
	s_nop 0
	v_mov_b32_e32 v68, v129
	v_mov_b32_e32 v69, v113
	v_pk_add_f32 v[66:67], v[68:69], v[66:67]
	s_waitcnt vmcnt(0) lgkmcnt(0)
	s_barrier
	s_nop 0
	v_pk_add_f32 v[66:67], v[66:67], v[66:67] op_sel:[0,1] op_sel_hi:[1,0]
	s_nop 0
	v_mov_b32_e32 v0, v66
	s_nop 1
	v_permlane32_swap_b32_e32 v66, v0
	v_add_f32_e32 v0, v66, v0
	v_add_f32_e32 v71, v203, v0
	v_cvt_pk_bf16_f32 v66, v114, v115
	v_cvt_pk_bf16_f32 v67, v116, v117
	v_cvt_pk_bf16_f32 v68, v118, v119
	v_cvt_pk_bf16_f32 v69, v120, v121
	v_cvt_pk_bf16_f32 v72, v122, v123
	v_cvt_pk_bf16_f32 v73, v124, v125
	v_cvt_pk_bf16_f32 v74, v126, v127
	v_cvt_pk_bf16_f32 v75, v128, v129
	v_cvt_pk_bf16_f32 v76, v98, v99
	v_cvt_pk_bf16_f32 v77, v100, v101
	v_cvt_pk_bf16_f32 v78, v102, v103
	v_cvt_pk_bf16_f32 v79, v104, v105
	v_cvt_pk_bf16_f32 v80, v106, v107
	v_cvt_pk_bf16_f32 v81, v108, v109
	v_cvt_pk_bf16_f32 v82, v110, v111
	v_cvt_pk_bf16_f32 v83, v112, v113
	s_nop 0
	v_permlane32_swap_b32_e32 v66, v68
	v_permlane32_swap_b32_e32 v67, v69
	v_permlane32_swap_b32_e32 v72, v74
	v_permlane32_swap_b32_e32 v73, v75
	v_permlane32_swap_b32_e32 v76, v78
	v_permlane32_swap_b32_e32 v77, v79
	v_permlane32_swap_b32_e32 v80, v82
	v_permlane32_swap_b32_e32 v81, v83
	s_cmp_lg_u32 s41, -1
	s_cselect_b32 s0, s41, 0
	s_addk_i32 s0, 0x4000
	v_add_u32_e32 v0, s0, v202
	ds_read_b64_tr_b16 v[84:85], v0 offset:0
	ds_read_b64_tr_b16 v[86:87], v0 offset:0x800
	ds_read_b64_tr_b16 v[88:89], v0 offset:0x1000
	ds_read_b64_tr_b16 v[90:91], v0 offset:0x1800
	ds_read_b64_tr_b16 v[92:93], v0 offset:0x2000
	ds_read_b64_tr_b16 v[94:95], v0 offset:0x2800
	ds_read_b64_tr_b16 v[96:97], v0 offset:0x3000
	ds_read_b64_tr_b16 v[98:99], v0 offset:0x3800
	s_waitcnt lgkmcnt(0)
	s_nop 0
	v_mfma_f32_32x32x16_bf16 v[50:65], v[66:69], v[84:87], v[50:65]
	ds_read_b64_tr_b16 v[84:85], v0 offset:0x200
	ds_read_b64_tr_b16 v[86:87], v0 offset:0xa00
	v_mfma_f32_32x32x16_bf16 v[50:65], v[72:75], v[88:91], v[50:65]
	ds_read_b64_tr_b16 v[88:89], v0 offset:0x1200
	ds_read_b64_tr_b16 v[90:91], v0 offset:0x1a00
	v_mfma_f32_32x32x16_bf16 v[50:65], v[76:79], v[92:95], v[50:65]
	ds_read_b64_tr_b16 v[92:93], v0 offset:0x2200
	ds_read_b64_tr_b16 v[94:95], v0 offset:0x2a00
	v_mfma_f32_32x32x16_bf16 v[50:65], v[80:83], v[96:99], v[50:65]
	ds_read_b64_tr_b16 v[96:97], v0 offset:0x3200
	ds_read_b64_tr_b16 v[98:99], v0 offset:0x3a00
	s_waitcnt lgkmcnt(0)
	v_mfma_f32_32x32x16_bf16 v[34:49], v[66:69], v[84:87], v[34:49]
	ds_read_b64_tr_b16 v[84:85], v0 offset:0x400
	ds_read_b64_tr_b16 v[86:87], v0 offset:0xc00
	v_mfma_f32_32x32x16_bf16 v[34:49], v[72:75], v[88:91], v[34:49]
	ds_read_b64_tr_b16 v[88:89], v0 offset:0x1400
	ds_read_b64_tr_b16 v[90:91], v0 offset:0x1c00
	v_mfma_f32_32x32x16_bf16 v[34:49], v[76:79], v[92:95], v[34:49]
	ds_read_b64_tr_b16 v[92:93], v0 offset:0x2400
	ds_read_b64_tr_b16 v[94:95], v0 offset:0x2c00
	v_mfma_f32_32x32x16_bf16 v[34:49], v[80:83], v[96:99], v[34:49]
	ds_read_b64_tr_b16 v[96:97], v0 offset:0x3400
	ds_read_b64_tr_b16 v[98:99], v0 offset:0x3c00
	s_waitcnt lgkmcnt(0)
	v_mfma_f32_32x32x16_bf16 v[18:33], v[66:69], v[84:87], v[18:33]
	ds_read_b64_tr_b16 v[84:85], v0 offset:0x600
	ds_read_b64_tr_b16 v[86:87], v0 offset:0xe00
	v_mfma_f32_32x32x16_bf16 v[18:33], v[72:75], v[88:91], v[18:33]
	ds_read_b64_tr_b16 v[88:89], v0 offset:0x1600
	ds_read_b64_tr_b16 v[90:91], v0 offset:0x1e00
	v_mfma_f32_32x32x16_bf16 v[18:33], v[76:79], v[92:95], v[18:33]
	ds_read_b64_tr_b16 v[92:93], v0 offset:0x2600
	ds_read_b64_tr_b16 v[94:95], v0 offset:0x2e00
	v_mfma_f32_32x32x16_bf16 v[18:33], v[80:83], v[96:99], v[18:33]
	ds_read_b64_tr_b16 v[96:97], v0 offset:0x3600
	ds_read_b64_tr_b16 v[98:99], v0 offset:0x3e00
	s_waitcnt lgkmcnt(0)
	v_mfma_f32_32x32x16_bf16 v[2:17], v[66:69], v[84:87], v[2:17]
	v_cmp_nlt_f32_e32 vcc, s27, v71
	v_cmp_ngt_f32_e64 s[0:1], s26, v71
	s_or_b64 s[2:3], vcc, s[0:1]
	v_mfma_f32_32x32x16_bf16 v[2:17], v[72:75], v[88:91], v[2:17]
	v_mfma_f32_32x32x16_bf16 v[2:17], v[76:79], v[92:95], v[2:17]
	v_mfma_f32_32x32x16_bf16 v[2:17], v[80:83], v[96:99], v[2:17]
	s_and_saveexec_b64 s[0:1], s[2:3]
	s_cbranch_execz .LBB0_422
	s_mov_b64 s[2:3], src_shared_base
	s_add_i32 s2, 0, 0x1d000
	s_cmp_lg_u32 s2, -1
	s_cselect_b32 s2, s2, 0
	s_cselect_b32 s3, s3, 0
	v_mov_b32_e32 v66, s2
	v_mov_b32_e32 v67, s3
	flat_store_dword v[66:67], v175 sc0 sc1
	s_waitcnt vmcnt(0)

; template <int DK, bool NOMAX> ...
;     ...
;   for (int d0 = 0; d0 < NS; ++d0) {
;     if (d0 == 0) { c0 = __builtin_amdgcn_mfma_f32_32x32x16_bf16(kf[0][0], qr[0], f32x16{}, 0, 0, 0); c1 = __builtin_amdgcn_mfma_f32_32x32x16_bf16(kf[0][1], qr[0], f32x16{}, 0, 0, 0); }
;     else { c0 = __builtin_amdgcn_mfma_f32_32x32x16_bf16(kf[d0 & 1][0], qr[d0], c0, 0, 0, 0); c1 = __builtin_amdgcn_mfma_f32_32x32x16_bf16(kf[d0 & 1][1], qr[d0], c1, 0, 0, 0); }
;     if (d0 + 2 < NS) KRD_(d0 & 1, d0 + 2);
;     if constexpr (NOMAX) { }
;     else {
; #pragma unroll
;     for (int r = d0 * RPS; r < (d0 + 1) * RPS; ++r) { p1[r] = __builtin_amdgcn_exp2f(p1[r]); psa += p0[r]; }
;     if (d0 > 0) {
; #pragma unroll
;       for (int r = (d0 - 1) * RPS; r < d0 * RPS; ++r) psb += p1[r]; } }
;     if constexpr (NOMAX) {
;       if (d0 == NS / 4 - 1) { PK4R(p0, 0, pa[0]); PIN(pa[0]); }
;       if (d0 == NS / 2 - 1) { PK4R(p0, 8, pa[1]); PIN(pa[1]); }
;       if (d0 == 3 * NS / 4 - 1) { PK4R(p1, 0, pa[2]); PIN(pa[2]); }
;       if (d0 == NS - 1) { PK4R(p1, 8, pa[3]); PIN(pa[3]); }
;     } else {
;     if (d0 == NS / 2 - 1) { PK4R(p0, 0, pa[0]); PIN(pa[0]); }
;     if (d0 == NS / 2) { PK4R(p0, 8, pa[1]); PIN(pa[1]); }
;     if (d0 == NS - 1) { PK4R(p1, 0, pa[2]); PIN(pa[2]); }
;     }
;     if (d0 == NS - 1) {
;       vl[0] = vtr(vp + v_rd_off(0, 0, 0)); vh[0] = vtr(vp + v_rd_off(0, 0, 1)); vl[1] = vtr(vp + v_rd_off(1, 0, 0)); vh[1] = vtr(vp + v_rd_off(1, 0, 1)); }
;     PIN(p1); PIN(psa); PIN(psb);
;     SBAR();
;   }
; template <int DK, bool NOMAX> ...
;     ...
;   for (int i = 0; i < 16; ++i) {
;     if (i + 2 < 16) VRD_((i + 2) % 3, i + 2);
;     if (i == 1) { if (dk) __builtin_amdgcn_global_load_lds((const unsigned*)gk0, lk, 16, 0, 0); }
;     if (i == 3) { if constexpr (DK == 128) { if (dk) __builtin_amdgcn_global_load_lds((const unsigned*)gk1, (lds_up)((lds_cp)lk + 8192), 16, 0, 0); } }
;     if (i == 5) { if (dv) __builtin_amdgcn_global_load_lds((const unsigned*)gv0, lv, 16, 0, 0); }
;     if (i == 7) { if (dv) __builtin_amdgcn_global_load_lds((const unsigned*)gv1, (lds_up)((lds_cp)lv + 8192), 16, 0, 0); }
;     if (i == 12 || i == 13) { const int cb_ = ((i - 12) * 16 + hi * 8) * 2;
;       if constexpr (DK == 128) { kf[i - 12][0] = *reinterpret_cast<const bf16x8*>(Kn + KSWZ128(r32, cb_)); kf[i - 12][1] = *reinterpret_cast<const bf16x8*>(Kn + KSWZ128(32 + r32, cb_)); }
.LBB0_462:
	s_mov_b32 s17, s15
	s_mov_b32 s15, s8
	s_add_i32 s8, s18, 0xffffc000
	s_and_b32 s38, s8, 0xc000
	s_add_i32 s8, s38, 0
	v_add_u32_e32 v0, s15, v204
	s_waitcnt lgkmcnt(0)
	v_mfma_f32_32x32x16_bf16 v[114:129], v[102:105], v[158:161], 0
	v_add_u32_e32 v188, s8, v218
	ds_read_b128 v[184:187], v188
	ds_read_b128 v[188:191], v188 offset:8192
	v_mfma_f32_32x32x16_bf16 v[98:113], v[98:101], v[158:161], 0
	v_mfma_f32_32x32x16_bf16 v[114:129], v[166:169], v[154:157], v[114:129]
	v_mfma_f32_32x32x16_bf16 v[98:113], v[162:165], v[154:157], v[98:113]
	v_add_u32_e32 v162, s8, v219
	ds_read_b128 v[166:169], v162
	ds_read_b128 v[226:229], v162 offset:8192
	v_cvt_pk_bf16_f32 v162, v82, v83
	v_cvt_pk_bf16_f32 v163, v84, v85
	v_cvt_pk_bf16_f32 v164, v86, v87
	v_cvt_pk_bf16_f32 v165, v88, v89
	s_nop 0
	v_permlane32_swap_b32_e32 v162, v164
	v_permlane32_swap_b32_e32 v163, v165
	s_waitcnt lgkmcnt(3)
	v_mfma_f32_32x32x16_bf16 v[114:129], v[184:187], v[150:153], v[114:129]
	v_add_u32_e32 v86, s8, v220
	ds_read_b128 v[82:85], v86
	ds_read_b128 v[86:89], v86 offset:8192
	s_waitcnt lgkmcnt(4)
	v_mfma_f32_32x32x16_bf16 v[98:113], v[188:191], v[150:153], v[98:113]
	s_waitcnt lgkmcnt(3)
	v_mfma_f32_32x32x16_bf16 v[114:129], v[166:169], v[146:149], v[114:129]
	v_add_u32_e32 v184, s8, v221
	ds_read_b128 v[166:169], v184
	ds_read_b128 v[184:187], v184 offset:8192
	v_cvt_pk_bf16_f32 v90, v90, v91
	v_cvt_pk_bf16_f32 v91, v92, v93
	v_cvt_pk_bf16_f32 v92, v94, v95
	v_cvt_pk_bf16_f32 v93, v96, v97
	s_waitcnt lgkmcnt(4)
	v_mfma_f32_32x32x16_bf16 v[98:113], v[226:229], v[146:149], v[98:113]
	v_permlane32_swap_b32_e32 v90, v92
	v_permlane32_swap_b32_e32 v91, v93
	s_waitcnt lgkmcnt(3)
	v_mfma_f32_32x32x16_bf16 v[114:129], v[82:85], v[142:145], v[114:129]
	s_waitcnt lgkmcnt(2)
	v_mfma_f32_32x32x16_bf16 v[98:113], v[86:89], v[142:145], v[98:113]
	v_add_u32_e32 v86, s8, v222
	ds_read_b128 v[82:85], v86
	ds_read_b128 v[94:97], v86 offset:8192
	s_waitcnt lgkmcnt(3)
	v_mfma_f32_32x32x16_bf16 v[114:129], v[166:169], v[138:141], v[114:129]
	v_add_u32_e32 v86, s8, v223
	s_waitcnt lgkmcnt(2)
	v_mfma_f32_32x32x16_bf16 v[98:113], v[184:187], v[138:141], v[98:113]
	ds_read_b128 v[166:169], v86
	ds_read_b128 v[184:187], v86 offset:8192
	v_cvt_pk_bf16_f32 v86, v66, v67
	v_cvt_pk_bf16_f32 v87, v68, v69
	v_cvt_pk_bf16_f32 v88, v70, v71
	v_cvt_pk_bf16_f32 v89, v72, v73
	s_nop 0
	v_permlane32_swap_b32_e32 v86, v88
	v_permlane32_swap_b32_e32 v87, v89
	s_waitcnt lgkmcnt(3)
	v_mfma_f32_32x32x16_bf16 v[114:129], v[82:85], v[130:133], v[114:129]
	s_waitcnt lgkmcnt(2)
	v_mfma_f32_32x32x16_bf16 v[98:113], v[94:97], v[130:133], v[98:113]
	v_cvt_pk_bf16_f32 v82, v74, v75
	v_cvt_pk_bf16_f32 v83, v76, v77
	v_cvt_pk_bf16_f32 v84, v78, v79
	v_cvt_pk_bf16_f32 v85, v80, v81
	s_waitcnt lgkmcnt(1)
	v_mfma_f32_32x32x16_bf16 v[114:129], v[166:169], v[134:137], v[114:129]
	v_permlane32_swap_b32_e32 v82, v84
	v_permlane32_swap_b32_e32 v83, v85
	s_cmp_gt_i32 s14, 61
	s_cbranch_scc1 .Lmy_mb0_b2_1
	s_waitcnt vmcnt(4) lgkmcnt(0)
	s_barrier
.Lmy_mbj_b2_1:
	ds_read_b64_tr_b16 v[166:167], v0
	ds_read_b64_tr_b16 v[168:169], v0 offset:2048
	ds_read_b64_tr_b16 v[94:95], v0 offset:512
	ds_read_b64_tr_b16 v[96:97], v0 offset:2560
	s_waitcnt lgkmcnt(4)
	v_mfma_f32_32x32x16_bf16 v[98:113], v[184:187], v[134:137], v[98:113]
	s_cmp_lt_u32 s14, 61
	s_cselect_b64 s[10:11], -1, 0
	s_cmp_gt_u32 s14, 60
	s_cselect_b64 s[8:9], -1, 0
	s_add_i32 s19, s18, 0x8000
	s_and_b32 s12, s19, 0xc000
	ds_read_b64_tr_b16 v[70:71], v0 offset:1024
	ds_read_b64_tr_b16 v[72:73], v0 offset:3072
	s_waitcnt lgkmcnt(4)
	v_mfma_f32_32x32x16_bf16 v[50:65], v[162:165], v[166:169], v[50:65]
	v_exp_f32_e32 v114, v114
	s_nop 0
	v_exp_f32_e32 v98, v98
	ds_read_b64_tr_b16 v[66:67], v0 offset:1536
	ds_read_b64_tr_b16 v[68:69], v0 offset:3584
	s_and_b64 vcc, exec, s[8:9]
	s_cbranch_vccnz .LBB0_464
	s_add_u32 vcc_lo, s0, s50
	s_addc_u32 vcc_hi, s1, s51
	s_add_i32 m0, s2, s12
	s_nop 0
	global_load_lds_dwordx4 v182, vcc

; template <int DK, bool NOMAX> ...
;     ...
;   for (int d0 = 0; d0 < NS; ++d0) {
;     if (d0 == 0) { c0 = __builtin_amdgcn_mfma_f32_32x32x16_bf16(kf[0][0], qr[0], f32x16{}, 0, 0, 0); c1 = __builtin_amdgcn_mfma_f32_32x32x16_bf16(kf[0][1], qr[0], f32x16{}, 0, 0, 0); }
;     else { c0 = __builtin_amdgcn_mfma_f32_32x32x16_bf16(kf[d0 & 1][0], qr[d0], c0, 0, 0, 0); c1 = __builtin_amdgcn_mfma_f32_32x32x16_bf16(kf[d0 & 1][1], qr[d0], c1, 0, 0, 0); }
;     if (d0 + 2 < NS) KRD_(d0 & 1, d0 + 2);
;     if constexpr (NOMAX) { }
;     else {
; #pragma unroll
;     for (int r = d0 * RPS; r < (d0 + 1) * RPS; ++r) { p1[r] = __builtin_amdgcn_exp2f(p1[r]); psa += p0[r]; }
;     if (d0 > 0) {
; #pragma unroll
;       for (int r = (d0 - 1) * RPS; r < d0 * RPS; ++r) psb += p1[r]; } }
;     if constexpr (NOMAX) {
;       if (d0 == NS / 4 - 1) { PK4R(p0, 0, pa[0]); PIN(pa[0]); }
;       if (d0 == NS / 2 - 1) { PK4R(p0, 8, pa[1]); PIN(pa[1]); }
;       if (d0 == 3 * NS / 4 - 1) { PK4R(p1, 0, pa[2]); PIN(pa[2]); }
;       if (d0 == NS - 1) { PK4R(p1, 8, pa[3]); PIN(pa[3]); }
;     } else {
;     if (d0 == NS / 2 - 1) { PK4R(p0, 0, pa[0]); PIN(pa[0]); }
;     if (d0 == NS / 2) { PK4R(p0, 8, pa[1]); PIN(pa[1]); }
;     if (d0 == NS - 1) { PK4R(p1, 0, pa[2]); PIN(pa[2]); }
;     }
;     if (d0 == NS - 1) {
;       vl[0] = vtr(vp + v_rd_off(0, 0, 0)); vh[0] = vtr(vp + v_rd_off(0, 0, 1)); vl[1] = vtr(vp + v_rd_off(1, 0, 0)); vh[1] = vtr(vp + v_rd_off(1, 0, 1)); }
;     PIN(p1); PIN(psa); PIN(psb);
;     SBAR();
;   }
; template <int DK, bool NOMAX> ...
;     ...
;   for (int i = 0; i < 16; ++i) {
;     if (i + 2 < 16) VRD_((i + 2) % 3, i + 2);
;     if (i == 1) { if (dk) __builtin_amdgcn_global_load_lds((const unsigned*)gk0, lk, 16, 0, 0); }
;     if (i == 3) { if constexpr (DK == 128) { if (dk) __builtin_amdgcn_global_load_lds((const unsigned*)gk1, (lds_up)((lds_cp)lk + 8192), 16, 0, 0); } }
;     if (i == 5) { if (dv) __builtin_amdgcn_global_load_lds((const unsigned*)gv0, lv, 16, 0, 0); }
;     if (i == 7) { if (dv) __builtin_amdgcn_global_load_lds((const unsigned*)gv1, (lds_up)((lds_cp)lv + 8192), 16, 0, 0); }
;     if (i == 12 || i == 13) { const int cb_ = ((i - 12) * 16 + hi * 8) * 2;
;       if constexpr (DK == 128) { kf[i - 12][0] = *reinterpret_cast<const bf16x8*>(Kn + KSWZ128(r32, cb_)); kf[i - 12][1] = *reinterpret_cast<const bf16x8*>(Kn + KSWZ128(32 + r32, cb_)); }
.LBB0_468:
.LBB0_470:
	v_add_u32_e32 v227, s17, v204
	v_mfma_f32_32x32x16_bf16 v[82:97], v[66:69], v[158:161], 0
	v_add_u32_e32 v232, s12, v218
	ds_read_b128 v[228:231], v232
	ds_read_b128 v[232:235], v232 offset:8192
	v_mfma_f32_32x32x16_bf16 v[66:81], v[70:73], v[158:161], 0
	v_mfma_f32_32x32x16_bf16 v[82:97], v[162:165], v[154:157], v[82:97]
	v_add_u32_e32 v162, s12, v219
	v_mfma_f32_32x32x16_bf16 v[66:81], v[166:169], v[154:157], v[66:81]
	ds_read_b128 v[166:169], v162
	ds_read_b128 v[236:239], v162 offset:8192
	v_cvt_pk_bf16_f32 v162, v114, v115
	v_cvt_pk_bf16_f32 v163, v116, v117
	v_cvt_pk_bf16_f32 v164, v118, v119
	v_cvt_pk_bf16_f32 v165, v120, v121
	s_nop 0
	v_permlane32_swap_b32_e32 v162, v164
	v_permlane32_swap_b32_e32 v163, v165
	s_waitcnt lgkmcnt(3)
	v_mfma_f32_32x32x16_bf16 v[82:97], v[228:231], v[150:153], v[82:97]
	v_add_u32_e32 v118, s12, v220
	ds_read_b128 v[114:117], v118
	ds_read_b128 v[118:121], v118 offset:8192
	s_waitcnt lgkmcnt(4)
	v_mfma_f32_32x32x16_bf16 v[66:81], v[232:235], v[150:153], v[66:81]
	s_waitcnt lgkmcnt(3)
	v_mfma_f32_32x32x16_bf16 v[82:97], v[166:169], v[146:149], v[82:97]
	v_add_u32_e32 v228, s12, v221
	ds_read_b128 v[166:169], v228
	ds_read_b128 v[228:231], v228 offset:8192
	v_cvt_pk_bf16_f32 v122, v122, v123
	v_cvt_pk_bf16_f32 v123, v124, v125
	v_cvt_pk_bf16_f32 v124, v126, v127
	v_cvt_pk_bf16_f32 v125, v128, v129
	s_waitcnt lgkmcnt(4)
	v_mfma_f32_32x32x16_bf16 v[66:81], v[236:239], v[146:149], v[66:81]
	v_permlane32_swap_b32_e32 v122, v124
	v_permlane32_swap_b32_e32 v123, v125
	s_waitcnt lgkmcnt(3)
	v_mfma_f32_32x32x16_bf16 v[82:97], v[114:117], v[142:145], v[82:97]
	s_waitcnt lgkmcnt(2)
	v_mfma_f32_32x32x16_bf16 v[66:81], v[118:121], v[142:145], v[66:81]
	v_add_u32_e32 v118, s12, v222
	ds_read_b128 v[114:117], v118
	ds_read_b128 v[126:129], v118 offset:8192
	s_waitcnt lgkmcnt(3)
	v_mfma_f32_32x32x16_bf16 v[82:97], v[166:169], v[138:141], v[82:97]
	v_add_u32_e32 v118, s12, v223
	s_waitcnt lgkmcnt(2)
	v_mfma_f32_32x32x16_bf16 v[66:81], v[228:231], v[138:141], v[66:81]
	ds_read_b128 v[166:169], v118
	ds_read_b128 v[228:231], v118 offset:8192
	v_cvt_pk_bf16_f32 v118, v98, v99
	v_cvt_pk_bf16_f32 v119, v100, v101
	v_cvt_pk_bf16_f32 v120, v102, v103
	v_cvt_pk_bf16_f32 v121, v104, v105
	s_nop 0
	v_permlane32_swap_b32_e32 v118, v120
	v_permlane32_swap_b32_e32 v119, v121
	s_waitcnt lgkmcnt(3)
	v_mfma_f32_32x32x16_bf16 v[82:97], v[114:117], v[130:133], v[82:97]
	s_waitcnt lgkmcnt(2)
	v_mfma_f32_32x32x16_bf16 v[66:81], v[126:129], v[130:133], v[66:81]
	v_cvt_pk_bf16_f32 v114, v106, v107
	v_cvt_pk_bf16_f32 v115, v108, v109
	v_cvt_pk_bf16_f32 v116, v110, v111
	v_cvt_pk_bf16_f32 v117, v112, v113
	s_waitcnt lgkmcnt(1)
	v_mfma_f32_32x32x16_bf16 v[82:97], v[166:169], v[134:137], v[82:97]
	v_permlane32_swap_b32_e32 v114, v116
	v_permlane32_swap_b32_e32 v115, v117
	s_cmp_gt_i32 s14, 60
	s_cbranch_scc1 .Lmy_mb0_b2_2
	s_waitcnt vmcnt(4) lgkmcnt(0)
	s_barrier
.Lmy_mbj_b2_2:
	ds_read_b64_tr_b16 v[166:167], v227
	ds_read_b64_tr_b16 v[168:169], v227 offset:2048
	ds_read_b64_tr_b16 v[126:127], v227 offset:512
	ds_read_b64_tr_b16 v[128:129], v227 offset:2560
	s_waitcnt lgkmcnt(4)
	v_mfma_f32_32x32x16_bf16 v[66:81], v[228:231], v[134:137], v[66:81]
	s_cmp_lt_u32 s14, 60
	s_cselect_b64 s[12:13], -1, 0
	s_cmp_gt_u32 s14, 59
	s_cselect_b64 s[10:11], -1, 0
	ds_read_b64_tr_b16 v[102:103], v227 offset:1024
	ds_read_b64_tr_b16 v[104:105], v227 offset:3072
	s_waitcnt lgkmcnt(4)
	v_mfma_f32_32x32x16_bf16 v[50:65], v[162:165], v[166:169], v[50:65]
	v_exp_f32_e32 v82, v82
	s_nop 2
	v_exp_f32_e32 v66, v66
	ds_read_b64_tr_b16 v[98:99], v227 offset:1536
	ds_read_b64_tr_b16 v[100:101], v227 offset:3584
	s_and_b64 vcc, exec, s[10:11]
	s_cbranch_vccnz .LBB0_472
	s_add_u32 vcc_lo, s0, s64
	s_addc_u32 vcc_hi, s1, s65
	s_add_i32 m0, s2, s38
	s_nop 0
	global_load_lds_dwordx4 v182, vcc

; template <int DK, bool NOMAX> ...
;     ...
;   for (int i = 0; i < 16; ++i) {
;     if (i + 2 < 16) VRD_((i + 2) % 3, i + 2);
;     if (i == 1) { if (dk) __builtin_amdgcn_global_load_lds((const unsigned*)gk0, lk, 16, 0, 0); }
;     if (i == 3) { if constexpr (DK == 128) { if (dk) __builtin_amdgcn_global_load_lds((const unsigned*)gk1, (lds_up)((lds_cp)lk + 8192), 16, 0, 0); } }
;     if (i == 5) { if (dv) __builtin_amdgcn_global_load_lds((const unsigned*)gv0, lv, 16, 0, 0); }
;     if (i == 7) { if (dv) __builtin_amdgcn_global_load_lds((const unsigned*)gv1, (lds_up)((lds_cp)lv + 8192), 16, 0, 0); }
;     if (i == 12 || i == 13) { const int cb_ = ((i - 12) * 16 + hi * 8) * 2;
;       if constexpr (DK == 128) { kf[i - 12][0] = *reinterpret_cast<const bf16x8*>(Kn + KSWZ128(r32, cb_)); kf[i - 12][1] = *reinterpret_cast<const bf16x8*>(Kn + KSWZ128(32 + r32, cb_)); }
;       else { kf[i - 12][0] = *reinterpret_cast<const bf16x8*>(Kn + KSWZ64(r32, cb_)); kf[i - 12][1] = *reinterpret_cast<const bf16x8*>(Kn + KSWZ64(32 + r32, cb_)); } }
;     SBAR();
;     o[i & 3] = __builtin_amdgcn_mfma_f32_32x32x16_bf16(pa[i >> 2], VFR_(i % 3), o[i & 3], 0, 0, 0);
;     if constexpr (NOMAX) { c0[i] = __builtin_amdgcn_exp2f(c0[i]); c1[i] = __builtin_amdgcn_exp2f(c1[i]); if (i > 0) { psa += c0[i - 1]; psb += c1[i - 1]; } PIN(c0); PIN(c1); PIN(psa); PIN(psb); }
;     else {
;     if (i == 0) { ma = max3f(c0[0], c0[1], c1[0]); mb = max3f(c0[2], c0[3], c1[1]); ma = max3f(ma, c1[2], c1[3]); }
;     if (i >= 1 && i <= 3) { const int r = 4 * i; ma = max3f(ma, c0[r], c0[r + 1]); mb = max3f(mb, c0[r + 2], c0[r + 3]); ma = max3f(ma, c1[r], c1[r + 1]); mb = max3f(mb, c1[r + 2], c1[r + 3]); }
;     if (i == 4) { float pmax = fmaxf(ma, mb);
;       { auto rr = __builtin_amdgcn_permlane32_swap(__float_as_uint(pmax), __float_as_uint(pmax), false, false);
;         pmax = fmaxf(__uint_as_float(rr[0]), __uint_as_float(rr[1])); }
;       pmax += cb;
;       const bool keep = __all(pmax - m_reg <= THR2);
;       const float mn = keep ? m_reg : fmaxf(m_reg, pmax);
;       alpha = __builtin_amdgcn_exp2f(m_reg - mn); m_reg = mn; mnC = cb - mn; }
;     if (i >= 5 && i <= 8) { const int r = 4 * (i - 5);
; #pragma unroll
;       for (int q = 0; q < 4; ++q) { c0[r + q] += mnC; c1[r + q] += mnC; } }
;     if (i >= 9) { const int r0 = (i - 9) * 2 + (i > 14 ? 1 : 0), n = i >= 14 ? 3 : 2;
; #pragma unroll
.LBB0_474:
	s_add_i32 s12, s18, 0x4000
	s_and_b32 s12, s12, 0xc000
	s_add_i32 s12, s12, 0
	s_waitcnt lgkmcnt(4)
	v_mfma_f32_32x32x16_bf16 v[2:17], v[162:165], v[98:101], v[2:17]
	v_exp_f32_e32 v85, v85
	v_exp_f32_e32 v69, v69
	v_add_f32_e32 v111, v68, v111
	v_add_f32_e32 v110, v84, v110
	ds_read_b64_tr_b16 v[98:99], v227 offset:5120
	ds_read_b64_tr_b16 v[100:101], v227 offset:7168
	s_waitcnt lgkmcnt(4)
	v_mfma_f32_32x32x16_bf16 v[50:65], v[122:125], v[106:109], v[50:65]
	v_exp_f32_e32 v86, v86
	v_exp_f32_e32 v70, v70
	v_add_f32_e32 v111, v69, v111
	v_add_f32_e32 v110, v85, v110
	s_add_u32 vcc_lo, s0, s24
	s_addc_u32 vcc_hi, s1, s25
	s_add_i32 s13, s3, s15
	s_mov_b32 m0, s13
	ds_read_b64_tr_b16 v[106:107], v227 offset:5632
	ds_read_b64_tr_b16 v[108:109], v227 offset:7680
	global_load_lds_dwordx4 v172, vcc
	s_waitcnt lgkmcnt(4)
	v_mfma_f32_32x32x16_bf16 v[34:49], v[122:125], v[102:105], v[34:49]
	v_exp_f32_e32 v87, v87
	v_exp_f32_e32 v71, v71
	v_add_f32_e32 v111, v70, v111
	v_add_f32_e32 v110, v86, v110
	ds_read_b64_tr_b16 v[102:103], v227 offset:8192
	ds_read_b64_tr_b16 v[104:105], v227 offset:10240
	s_waitcnt lgkmcnt(4)
	v_mfma_f32_32x32x16_bf16 v[18:33], v[122:125], v[98:101], v[18:33]
	v_exp_f32_e32 v88, v88
	v_exp_f32_e32 v72, v72
	v_add_f32_e32 v111, v71, v111
	v_add_f32_e32 v110, v87, v110
	s_add_i32 m0, s13, 0x2000
	ds_read_b64_tr_b16 v[98:99], v227 offset:8704
	ds_read_b64_tr_b16 v[100:101], v227 offset:10752
	global_load_lds_dwordx4 v170, vcc
	s_waitcnt lgkmcnt(4)
	v_mfma_f32_32x32x16_bf16 v[2:17], v[122:125], v[106:109], v[2:17]
	v_exp_f32_e32 v89, v89
	v_exp_f32_e32 v73, v73
	v_add_f32_e32 v111, v72, v111
	v_add_f32_e32 v110, v88, v110
	ds_read_b64_tr_b16 v[106:107], v227 offset:9216
	ds_read_b64_tr_b16 v[108:109], v227 offset:11264
	s_waitcnt lgkmcnt(4)
	v_mfma_f32_32x32x16_bf16 v[50:65], v[118:121], v[102:105], v[50:65]
	v_exp_f32_e32 v90, v90
	v_exp_f32_e32 v74, v74
	v_add_f32_e32 v111, v73, v111
	v_add_f32_e32 v110, v89, v110
	ds_read_b64_tr_b16 v[102:103], v227 offset:9728
	ds_read_b64_tr_b16 v[104:105], v227 offset:11776
	s_waitcnt lgkmcnt(4)
	v_mfma_f32_32x32x16_bf16 v[34:49], v[118:121], v[98:101], v[34:49]
	v_exp_f32_e32 v91, v91
	v_exp_f32_e32 v75, v75
	v_add_f32_e32 v98, v74, v111
	v_add_f32_e32 v99, v90, v110
	ds_read_b64_tr_b16 v[110:111], v227 offset:12288
	ds_read_b64_tr_b16 v[112:113], v227 offset:14336
	s_waitcnt lgkmcnt(4)
	v_mfma_f32_32x32x16_bf16 v[18:33], v[118:121], v[106:109], v[18:33]
	v_exp_f32_e32 v92, v92
	v_exp_f32_e32 v76, v76
	v_add_f32_e32 v98, v75, v98
	v_add_f32_e32 v99, v91, v99
	ds_read_b64_tr_b16 v[106:107], v227 offset:12800
	ds_read_b64_tr_b16 v[108:109], v227 offset:14848
	s_waitcnt lgkmcnt(4)
	v_mfma_f32_32x32x16_bf16 v[2:17], v[118:121], v[102:105], v[2:17]
	v_exp_f32_e32 v93, v93
	v_exp_f32_e32 v77, v77
	v_add_f32_e32 v122, v76, v98
	v_add_f32_e32 v123, v92, v99
	v_add_u32_e32 v98, s12, v224
	ds_read_b64_tr_b16 v[118:119], v227 offset:13312
	ds_read_b64_tr_b16 v[120:121], v227 offset:15360
	ds_read_b128 v[102:105], v98
	ds_read_b128 v[98:101], v98 offset:8192
	s_waitcnt lgkmcnt(6)
	v_mfma_f32_32x32x16_bf16 v[50:65], v[114:117], v[110:113], v[50:65]
	v_exp_f32_e32 v94, v94
	v_exp_f32_e32 v78, v78
	v_add_f32_e32 v122, v77, v122
	v_add_f32_e32 v123, v93, v123
	v_add_u32_e32 v124, s12, v225
	ds_read_b64_tr_b16 v[110:111], v227 offset:13824
	ds_read_b64_tr_b16 v[112:113], v227 offset:15872
	ds_read_b128 v[166:169], v124
	ds_read_b128 v[162:165], v124 offset:8192
	s_waitcnt lgkmcnt(8)
	v_mfma_f32_32x32x16_bf16 v[34:49], v[114:117], v[106:109], v[34:49]
	v_exp_f32_e32 v95, v95
	v_exp_f32_e32 v79, v79
	v_add_f32_e32 v106, v78, v122
	v_add_f32_e32 v107, v94, v123
	s_waitcnt lgkmcnt(6)
	v_mfma_f32_32x32x16_bf16 v[18:33], v[114:117], v[118:121], v[18:33]
	v_exp_f32_e32 v96, v96
	v_exp_f32_e32 v80, v80
	v_add_f32_e32 v106, v79, v106
	v_add_f32_e32 v107, v95, v107
	s_waitcnt lgkmcnt(2)
	v_mfma_f32_32x32x16_bf16 v[2:17], v[114:117], v[110:113], v[2:17]
	v_exp_f32_e32 v97, v97
	v_exp_f32_e32 v81, v81
	v_add_f32_e32 v106, v80, v106
	v_add_f32_e32 v107, v96, v107
	s_nop 0
	v_add_f32_e32 v107, v97, v107
	v_add_f32_e32 v106, v81, v106
	v_add_f32_e32 v106, v107, v106
	v_mov_b32_e32 v107, v106
	s_nop 1
	v_permlane32_swap_b32_e32 v106, v107
	s_mov_b64 s[12:13], -1
	s_waitcnt lgkmcnt(0)
.LBB0_476:
.LBB0_478:
	v_add_f32_e32 v0, v0, v226
	s_add_i32 s14, s14, 2
	v_add_f32_e32 v0, v203, v0
	v_add_f32_e32 v106, v106, v107
	s_add_u32 s0, s0, 0x10000
	s_addc_u32 s1, s1, 0
	s_andn2_b64 vcc, exec, s[8:9]
	v_add_f32_e32 v203, v0, v106
	s_cbranch_vccz .LBB0_480
	s_mov_b32 s18, s19
	s_mov_b32 s8, s16
	s_mov_b32 s16, s17
	s_branch .LBB0_462

; template <int DK, bool NOMAX> ...
;     ...
;   for (int d0 = 0; d0 < NS; ++d0) {
;     if (d0 == 0) { c0 = __builtin_amdgcn_mfma_f32_32x32x16_bf16(kf[0][0], qr[0], f32x16{}, 0, 0, 0); c1 = __builtin_amdgcn_mfma_f32_32x32x16_bf16(kf[0][1], qr[0], f32x16{}, 0, 0, 0); }
;     else { c0 = __builtin_amdgcn_mfma_f32_32x32x16_bf16(kf[d0 & 1][0], qr[d0], c0, 0, 0, 0); c1 = __builtin_amdgcn_mfma_f32_32x32x16_bf16(kf[d0 & 1][1], qr[d0], c1, 0, 0, 0); }
;     if (d0 + 2 < NS) KRD_(d0 & 1, d0 + 2);
;     if constexpr (NOMAX) { }
;     else {
; #pragma unroll
;     for (int r = d0 * RPS; r < (d0 + 1) * RPS; ++r) { p1[r] = __builtin_amdgcn_exp2f(p1[r]); psa += p0[r]; }
;     if (d0 > 0) {
; #pragma unroll
;       for (int r = (d0 - 1) * RPS; r < d0 * RPS; ++r) psb += p1[r]; } }
;     if constexpr (NOMAX) {
;       if (d0 == NS / 4 - 1) { PK4R(p0, 0, pa[0]); PIN(pa[0]); }
;       if (d0 == NS / 2 - 1) { PK4R(p0, 8, pa[1]); PIN(pa[1]); }
;       if (d0 == 3 * NS / 4 - 1) { PK4R(p1, 0, pa[2]); PIN(pa[2]); }
;       if (d0 == NS - 1) { PK4R(p1, 8, pa[3]); PIN(pa[3]); }
;     } else {
;     if (d0 == NS / 2 - 1) { PK4R(p0, 0, pa[0]); PIN(pa[0]); }
;     if (d0 == NS / 2) { PK4R(p0, 8, pa[1]); PIN(pa[1]); }
;     if (d0 == NS - 1) { PK4R(p1, 0, pa[2]); PIN(pa[2]); }
;     }
;     if (d0 == NS - 1) {
;       vl[0] = vtr(vp + v_rd_off(0, 0, 0)); vh[0] = vtr(vp + v_rd_off(0, 0, 1)); vl[1] = vtr(vp + v_rd_off(1, 0, 0)); vh[1] = vtr(vp + v_rd_off(1, 0, 1)); }
;     PIN(p1); PIN(psa); PIN(psb);
;     SBAR();
;   }
; template <int DK, bool NOMAX> ...
;     ...
;   for (int i = 0; i < 16; ++i) {
;     if (i + 2 < 16) VRD_((i + 2) % 3, i + 2);
;     if (i == 1) { if (dk) __builtin_amdgcn_global_load_lds((const unsigned*)gk0, lk, 16, 0, 0); }
;     if (i == 3) { if constexpr (DK == 128) { if (dk) __builtin_amdgcn_global_load_lds((const unsigned*)gk1, (lds_up)((lds_cp)lk + 8192), 16, 0, 0); } }
;     if (i == 5) { if (dv) __builtin_amdgcn_global_load_lds((const unsigned*)gv0, lv, 16, 0, 0); }
;     if (i == 7) { if (dv) __builtin_amdgcn_global_load_lds((const unsigned*)gv1, (lds_up)((lds_cp)lv + 8192), 16, 0, 0); }
;     if (i == 12 || i == 13) { const int cb_ = ((i - 12) * 16 + hi * 8) * 2;
;       if constexpr (DK == 128) { kf[i - 12][0] = *reinterpret_cast<const bf16x8*>(Kn + KSWZ128(r32, cb_)); kf[i - 12][1] = *reinterpret_cast<const bf16x8*>(Kn + KSWZ128(32 + r32, cb_)); }
.LBB0_480:
	v_add3_u32 v0, 0, v217, v205
	ds_read_b128 v[170:173], v0 offset:49152
	ds_read_b128 v[180:183], v216 offset:57344
	v_mov_b32_e32 v0, v1
	v_mov_b32_e32 v188, v1
	v_mfma_f32_32x32x16_bf16 v[114:129], v[102:105], v[158:161], 0
	v_mfma_f32_32x32x16_bf16 v[98:113], v[98:101], v[158:161], 0
	v_mfma_f32_32x32x16_bf16 v[98:113], v[162:165], v[154:157], v[98:113]
	v_add3_u32 v162, 0, v215, v205
	v_mfma_f32_32x32x16_bf16 v[114:129], v[166:169], v[154:157], v[114:129]
	ds_read_b128 v[166:169], v162 offset:49152
	ds_read_b128 v[184:187], v214 offset:57344
	v_cvt_pk_bf16_f32 v162, v82, v83
	v_cvt_pk_bf16_f32 v163, v84, v85
	v_cvt_pk_bf16_f32 v164, v86, v87
	v_cvt_pk_bf16_f32 v165, v88, v89
	s_nop 0
	v_permlane32_swap_b32_e32 v162, v164
	v_permlane32_swap_b32_e32 v163, v165
	v_add3_u32 v82, 0, v213, v205
	ds_read_b128 v[82:85], v82 offset:49152
	ds_read_b128 v[86:89], v212 offset:57344
	s_waitcnt lgkmcnt(5)
	v_mfma_f32_32x32x16_bf16 v[114:129], v[170:173], v[150:153], v[114:129]
	s_waitcnt lgkmcnt(4)
	v_mfma_f32_32x32x16_bf16 v[98:113], v[180:183], v[150:153], v[98:113]
	s_waitcnt lgkmcnt(3)
	v_mfma_f32_32x32x16_bf16 v[114:129], v[166:169], v[146:149], v[114:129]
	v_add3_u32 v166, 0, v211, v205
	ds_read_b128 v[166:169], v166 offset:49152
	ds_read_b128 v[170:173], v210 offset:57344
	v_cvt_pk_bf16_f32 v90, v90, v91
	v_cvt_pk_bf16_f32 v91, v92, v93
	v_cvt_pk_bf16_f32 v92, v94, v95
	v_cvt_pk_bf16_f32 v93, v96, v97
	s_nop 0
	v_permlane32_swap_b32_e32 v90, v92
	v_permlane32_swap_b32_e32 v91, v93
	s_waitcnt lgkmcnt(4)
	v_mfma_f32_32x32x16_bf16 v[98:113], v[184:187], v[146:149], v[98:113]
	s_waitcnt lgkmcnt(3)
	v_mfma_f32_32x32x16_bf16 v[114:129], v[82:85], v[142:145], v[114:129]
	v_add3_u32 v82, 0, v209, v205
	ds_read_b128 v[82:85], v82 offset:49152
	ds_read_b128 v[94:97], v208 offset:57344
	s_waitcnt lgkmcnt(4)
	v_mfma_f32_32x32x16_bf16 v[98:113], v[86:89], v[142:145], v[98:113]
	v_add3_u32 v86, 0, v207, v205
	s_waitcnt lgkmcnt(3)
	v_mfma_f32_32x32x16_bf16 v[114:129], v[166:169], v[138:141], v[114:129]
	s_waitcnt lgkmcnt(2)
	v_mfma_f32_32x32x16_bf16 v[98:113], v[170:173], v[138:141], v[98:113]
	ds_read_b128 v[166:169], v86 offset:49152
	ds_read_b128 v[170:173], v206 offset:57344
	v_cvt_pk_bf16_f32 v86, v66, v67
	v_cvt_pk_bf16_f32 v87, v68, v69
	v_cvt_pk_bf16_f32 v88, v70, v71
	v_cvt_pk_bf16_f32 v89, v72, v73
	s_nop 0
	v_permlane32_swap_b32_e32 v86, v88
	v_permlane32_swap_b32_e32 v87, v89
	s_waitcnt lgkmcnt(3)
	v_mfma_f32_32x32x16_bf16 v[114:129], v[82:85], v[130:133], v[114:129]
	s_waitcnt lgkmcnt(2)
	v_mfma_f32_32x32x16_bf16 v[98:113], v[94:97], v[130:133], v[98:113]
	v_cvt_pk_bf16_f32 v82, v74, v75
	v_cvt_pk_bf16_f32 v83, v76, v77
	v_cvt_pk_bf16_f32 v84, v78, v79
	v_cvt_pk_bf16_f32 v85, v80, v81
	s_waitcnt lgkmcnt(1)
	v_mfma_f32_32x32x16_bf16 v[114:129], v[166:169], v[134:137], v[114:129]
	v_permlane32_swap_b32_e32 v82, v84
	v_permlane32_swap_b32_e32 v83, v85
	s_waitcnt vmcnt(0) lgkmcnt(0)
	s_barrier
	ds_read_b64_tr_b16 v[94:95], v204 offset:32768
	ds_read_b64_tr_b16 v[96:97], v204 offset:34816
	ds_read_b64_tr_b16 v[166:167], v204 offset:33280
	ds_read_b64_tr_b16 v[168:169], v204 offset:35328
	s_waitcnt lgkmcnt(4)
	v_mfma_f32_32x32x16_bf16 v[98:113], v[170:173], v[134:137], v[98:113]
	ds_read_b64_tr_b16 v[66:67], v204 offset:33792
	ds_read_b64_tr_b16 v[68:69], v204 offset:35840
	s_waitcnt lgkmcnt(4)
	v_mfma_f32_32x32x16_bf16 v[50:65], v[162:165], v[94:97], v[50:65]
	s_nop 0
	v_exp_f32_e32 v114, v114
	s_nop 5
	v_exp_f32_e32 v98, v98
	v_mov_b32_e32 v0, v1
	v_mov_b32_e32 v74, v1
	ds_read_b64_tr_b16 v[70:71], v204 offset:34304
	ds_read_b64_tr_b16 v[72:73], v204 offset:36352
	s_waitcnt lgkmcnt(4)
	v_mfma_f32_32x32x16_bf16 v[34:49], v[162:165], v[166:169], v[34:49]
	v_exp_f32_e32 v115, v115
	v_exp_f32_e32 v99, v99
	v_add_f32_e32 v78, v98, v74
	v_add_f32_e32 v0, v114, v0
	ds_read_b64_tr_b16 v[74:75], v204 offset:36864
	ds_read_b64_tr_b16 v[76:77], v204 offset:38912
	s_waitcnt lgkmcnt(4)
	v_mfma_f32_32x32x16_bf16 v[18:33], v[162:165], v[66:69], v[18:33]
	v_exp_f32_e32 v116, v116
	v_exp_f32_e32 v100, v100
	v_add_f32_e32 v78, v99, v78
	v_add_f32_e32 v0, v115, v0
	ds_read_b64_tr_b16 v[66:67], v204 offset:37376
	ds_read_b64_tr_b16 v[68:69], v204 offset:39424
	s_waitcnt lgkmcnt(4)
	v_mfma_f32_32x32x16_bf16 v[2:17], v[162:165], v[70:73], v[2:17]
	v_exp_f32_e32 v117, v117
	v_exp_f32_e32 v101, v101
	v_add_f32_e32 v78, v100, v78
	v_add_f32_e32 v0, v116, v0
	ds_read_b64_tr_b16 v[70:71], v204 offset:37888
	ds_read_b64_tr_b16 v[72:73], v204 offset:39936
	s_waitcnt lgkmcnt(4)
	v_mfma_f32_32x32x16_bf16 v[50:65], v[90:93], v[74:77], v[50:65]
	v_exp_f32_e32 v118, v118
	v_exp_f32_e32 v102, v102
	v_add_f32_e32 v78, v101, v78
	v_add_f32_e32 v0, v117, v0
	ds_read_b64_tr_b16 v[74:75], v204 offset:38400
	ds_read_b64_tr_b16 v[76:77], v204 offset:40448
	s_waitcnt lgkmcnt(4)
	v_mfma_f32_32x32x16_bf16 v[34:49], v[90:93], v[66:69], v[34:49]
	v_exp_f32_e32 v119, v119
	v_exp_f32_e32 v103, v103
	v_add_f32_e32 v78, v102, v78
	v_add_f32_e32 v0, v118, v0
	ds_read_b64_tr_b16 v[66:67], v204 offset:40960
	ds_read_b64_tr_b16 v[68:69], v204 offset:43008
	s_waitcnt lgkmcnt(4)
	v_mfma_f32_32x32x16_bf16 v[18:33], v[90:93], v[70:73], v[18:33]
	v_exp_f32_e32 v120, v120
	v_exp_f32_e32 v104, v104
	v_add_f32_e32 v78, v103, v78
	v_add_f32_e32 v0, v119, v0
	ds_read_b64_tr_b16 v[70:71], v204 offset:41472
	ds_read_b64_tr_b16 v[72:73], v204 offset:43520
	s_waitcnt lgkmcnt(4)
	v_mfma_f32_32x32x16_bf16 v[2:17], v[90:93], v[74:77], v[2:17]
	v_exp_f32_e32 v121, v121
	v_exp_f32_e32 v105, v105
	v_add_f32_e32 v78, v104, v78
	v_add_f32_e32 v0, v120, v0
	ds_read_b64_tr_b16 v[74:75], v204 offset:41984
	ds_read_b64_tr_b16 v[76:77], v204 offset:44032
	s_waitcnt lgkmcnt(4)
; #define SBAR() __builtin_amdgcn_sched_barrier(0)
; template <int D0> __device__ __forceinline__ void pv_one(f32x16& od, int vb, bf16x8 pa0, bf16x8 pa1, bf16x8 pa2, bf16x8 pa3) {
;   const s16x4 l0 = tr_read<v_rd_off(D0, 0, 0)>(vb), h0 = tr_read<v_rd_off(D0, 0, 1)>(vb), l1 = tr_read<v_rd_off(D0, 1, 0)>(vb), h1 = tr_read<v_rd_off(D0, 1, 1)>(vb);
;   const s16x4 l2 = tr_read<v_rd_off(D0, 2, 0)>(vb), h2 = tr_read<v_rd_off(D0, 2, 1)>(vb), l3 = tr_read<v_rd_off(D0, 3, 0)>(vb), h3 = tr_read<v_rd_off(D0, 3, 1)>(vb);
;   asm volatile("s_waitcnt lgkmcnt(0)" ::: "memory"); SBAR();
;     ...
;   od = __builtin_amdgcn_mfma_f32_32x32x16_bf16(pa0, PK(l0, h0), od, 0, 0, 0);
;   od = __builtin_amdgcn_mfma_f32_32x32x16_bf16(pa1, PK(l1, h1), od, 0, 0, 0);
;   od = __builtin_amdgcn_mfma_f32_32x32x16_bf16(pa2, PK(l2, h2), od, 0, 0, 0);
;   od = __builtin_amdgcn_mfma_f32_32x32x16_bf16(pa3, PK(l3, h3), od, 0, 0, 0);
;     ...
; }
; __device__ __forceinline__ void pv_d0(f32x16* o, int vb, bf16x8 pa0, bf16x8 pa1, bf16x8 pa2, bf16x8 pa3) {
;   pv_one<0>(o[0], vb, pa0, pa1, pa2, pa3); pv_one<1>(o[1], vb, pa0, pa1, pa2, pa3); pv_one<2>(o[2], vb, pa0, pa1, pa2, pa3); pv_one<3>(o[3], vb, pa0, pa1, pa2, pa3);
; template <int DK, int LDK, bool BIAS, bool NOMAX> ...
;     ...
;   STEPT(pB0, pB1, pA0, pA1, alA, alB, NT - 1);
;   if constexpr (NOMAX) { PK4R(pB0, 0, pa[0]); PK4R(pB0, 8, pa[1]); PK4R(pB1, 0, pa[2]); PK4R(pB1, 8, pa[3]); }
;   else finishSM<false>(pB0, pB1, alB, l_reg, pa[0], pa[1], pa[2], pa[3]);
;   SBAR();
;   pv_d0(o, vb0 + sp, pa[0], pa[1], pa[2], pa[3]);
;   l_out = l_reg;
	v_mfma_f32_32x32x16_bf16 v[50:65], v[86:89], v[66:69], v[50:65]
	v_exp_f32_e32 v122, v122
	v_exp_f32_e32 v106, v106
	v_add_f32_e32 v78, v105, v78
	v_add_f32_e32 v0, v121, v0
	ds_read_b64_tr_b16 v[66:67], v204 offset:42496
	ds_read_b64_tr_b16 v[68:69], v204 offset:44544
	s_waitcnt lgkmcnt(4)
	v_mfma_f32_32x32x16_bf16 v[34:49], v[86:89], v[70:73], v[34:49]
	v_exp_f32_e32 v123, v123
	v_exp_f32_e32 v107, v107
	v_add_f32_e32 v78, v106, v78
	v_add_f32_e32 v0, v122, v0
	ds_read_b64_tr_b16 v[70:71], v204 offset:45056
	ds_read_b64_tr_b16 v[72:73], v204 offset:47104
	s_waitcnt lgkmcnt(4)
	v_mfma_f32_32x32x16_bf16 v[18:33], v[86:89], v[74:77], v[18:33]
	v_exp_f32_e32 v124, v124
	v_exp_f32_e32 v108, v108
	v_add_f32_e32 v78, v107, v78
	v_add_f32_e32 v0, v123, v0
	ds_read_b64_tr_b16 v[74:75], v204 offset:45568
	ds_read_b64_tr_b16 v[76:77], v204 offset:47616
	s_waitcnt lgkmcnt(4)
	v_mfma_f32_32x32x16_bf16 v[2:17], v[86:89], v[66:69], v[2:17]
	v_exp_f32_e32 v125, v125
	v_exp_f32_e32 v109, v109
	v_add_f32_e32 v78, v108, v78
	v_add_f32_e32 v0, v124, v0
	ds_read_b64_tr_b16 v[66:67], v204 offset:46080
	ds_read_b64_tr_b16 v[68:69], v204 offset:48128
	s_waitcnt lgkmcnt(4)
	v_mfma_f32_32x32x16_bf16 v[50:65], v[82:85], v[70:73], v[50:65]
	v_exp_f32_e32 v126, v126
	v_exp_f32_e32 v110, v110
	v_add_f32_e32 v78, v109, v78
	v_add_f32_e32 v0, v125, v0
	ds_read_b64_tr_b16 v[70:71], v204 offset:46592
	ds_read_b64_tr_b16 v[72:73], v204 offset:48640
	s_waitcnt lgkmcnt(4)
	v_mfma_f32_32x32x16_bf16 v[34:49], v[82:85], v[74:77], v[34:49]
	v_exp_f32_e32 v127, v127
	v_exp_f32_e32 v111, v111
	v_add_f32_e32 v74, v110, v78
	v_add_f32_e32 v0, v126, v0
	s_waitcnt lgkmcnt(2)
	v_mfma_f32_32x32x16_bf16 v[18:33], v[82:85], v[66:69], v[18:33]
	v_exp_f32_e32 v128, v128
	v_exp_f32_e32 v112, v112
	v_add_f32_e32 v66, v111, v74
	v_add_f32_e32 v0, v127, v0
	s_waitcnt lgkmcnt(0)
	v_mfma_f32_32x32x16_bf16 v[2:17], v[82:85], v[70:73], v[2:17]
	v_exp_f32_e32 v129, v129
	v_exp_f32_e32 v113, v113
	v_add_f32_e32 v67, v112, v66
	v_add_f32_e32 v66, v128, v0
	s_nop 0
	v_mov_b32_e32 v68, v129
	v_mov_b32_e32 v69, v113
	v_pk_add_f32 v[66:67], v[68:69], v[66:67]
	s_waitcnt vmcnt(0) lgkmcnt(0)
	s_barrier
	s_cmp_lg_u32 s41, -1
	v_pk_add_f32 v[66:67], v[66:67], v[66:67] op_sel:[0,1] op_sel_hi:[1,0]
	s_cselect_b32 s0, s41, 0
	v_mov_b32_e32 v0, v66
	s_nop 1
	v_permlane32_swap_b32_e32 v66, v0
	v_add_f32_e32 v0, v66, v0
	v_add_f32_e32 v71, v203, v0
	v_cvt_pk_bf16_f32 v66, v114, v115
	v_cvt_pk_bf16_f32 v67, v116, v117
	v_cvt_pk_bf16_f32 v68, v118, v119
	v_cvt_pk_bf16_f32 v69, v120, v121
	v_cvt_pk_bf16_f32 v72, v122, v123
	v_cvt_pk_bf16_f32 v73, v124, v125
	v_cvt_pk_bf16_f32 v74, v126, v127
	v_cvt_pk_bf16_f32 v75, v128, v129
	v_cvt_pk_bf16_f32 v76, v98, v99
	v_cvt_pk_bf16_f32 v77, v100, v101
	v_cvt_pk_bf16_f32 v78, v102, v103
	v_cvt_pk_bf16_f32 v79, v104, v105
	v_cvt_pk_bf16_f32 v80, v106, v107
	v_cvt_pk_bf16_f32 v81, v108, v109
	v_cvt_pk_bf16_f32 v82, v110, v111
	v_cvt_pk_bf16_f32 v83, v112, v113
	v_add_u32_e32 v0, s0, v202
	v_permlane32_swap_b32_e32 v66, v68
	v_permlane32_swap_b32_e32 v67, v69
	v_permlane32_swap_b32_e32 v72, v74
	v_permlane32_swap_b32_e32 v73, v75
	v_permlane32_swap_b32_e32 v76, v78
	v_permlane32_swap_b32_e32 v77, v79
	v_permlane32_swap_b32_e32 v80, v82
	v_permlane32_swap_b32_e32 v81, v83
	ds_read_b64_tr_b16 v[84:85], v0 offset:0
	ds_read_b64_tr_b16 v[86:87], v0 offset:0x800
	ds_read_b64_tr_b16 v[88:89], v0 offset:0x1000
	ds_read_b64_tr_b16 v[90:91], v0 offset:0x1800
	ds_read_b64_tr_b16 v[92:93], v0 offset:0x2000
	ds_read_b64_tr_b16 v[94:95], v0 offset:0x2800
	ds_read_b64_tr_b16 v[96:97], v0 offset:0x3000
	ds_read_b64_tr_b16 v[98:99], v0 offset:0x3800
	s_waitcnt lgkmcnt(0)
	s_nop 0
	v_mfma_f32_32x32x16_bf16 v[50:65], v[66:69], v[84:87], v[50:65]
	ds_read_b64_tr_b16 v[84:85], v0 offset:0x200
	ds_read_b64_tr_b16 v[86:87], v0 offset:0xa00
	v_mfma_f32_32x32x16_bf16 v[50:65], v[72:75], v[88:91], v[50:65]
	ds_read_b64_tr_b16 v[88:89], v0 offset:0x1200
	ds_read_b64_tr_b16 v[90:91], v0 offset:0x1a00
	v_mfma_f32_32x32x16_bf16 v[50:65], v[76:79], v[92:95], v[50:65]
	ds_read_b64_tr_b16 v[92:93], v0 offset:0x2200
	ds_read_b64_tr_b16 v[94:95], v0 offset:0x2a00
	v_mfma_f32_32x32x16_bf16 v[50:65], v[80:83], v[96:99], v[50:65]
	ds_read_b64_tr_b16 v[96:97], v0 offset:0x3200
	ds_read_b64_tr_b16 v[98:99], v0 offset:0x3a00
	s_waitcnt lgkmcnt(0)
	v_mfma_f32_32x32x16_bf16 v[34:49], v[66:69], v[84:87], v[34:49]
	ds_read_b64_tr_b16 v[84:85], v0 offset:0x400
	ds_read_b64_tr_b16 v[86:87], v0 offset:0xc00
	v_mfma_f32_32x32x16_bf16 v[34:49], v[72:75], v[88:91], v[34:49]
	ds_read_b64_tr_b16 v[88:89], v0 offset:0x1400
	ds_read_b64_tr_b16 v[90:91], v0 offset:0x1c00
	v_mfma_f32_32x32x16_bf16 v[34:49], v[76:79], v[92:95], v[34:49]
	ds_read_b64_tr_b16 v[92:93], v0 offset:0x2400
	ds_read_b64_tr_b16 v[94:95], v0 offset:0x2c00
	v_mfma_f32_32x32x16_bf16 v[34:49], v[80:83], v[96:99], v[34:49]
	ds_read_b64_tr_b16 v[96:97], v0 offset:0x3400
	ds_read_b64_tr_b16 v[98:99], v0 offset:0x3c00
	s_waitcnt lgkmcnt(0)
	v_mfma_f32_32x32x16_bf16 v[18:33], v[66:69], v[84:87], v[18:33]
	ds_read_b64_tr_b16 v[84:85], v0 offset:0x600
	ds_read_b64_tr_b16 v[86:87], v0 offset:0xe00
	v_mfma_f32_32x32x16_bf16 v[18:33], v[72:75], v[88:91], v[18:33]
	ds_read_b64_tr_b16 v[88:89], v0 offset:0x1600
	ds_read_b64_tr_b16 v[90:91], v0 offset:0x1e00
	v_mfma_f32_32x32x16_bf16 v[18:33], v[76:79], v[92:95], v[18:33]
	ds_read_b64_tr_b16 v[92:93], v0 offset:0x2600
	ds_read_b64_tr_b16 v[94:95], v0 offset:0x2e00
	v_mfma_f32_32x32x16_bf16 v[18:33], v[80:83], v[96:99], v[18:33]
	ds_read_b64_tr_b16 v[96:97], v0 offset:0x3600
	ds_read_b64_tr_b16 v[98:99], v0 offset:0x3e00
	s_waitcnt lgkmcnt(0)
	v_mfma_f32_32x32x16_bf16 v[2:17], v[66:69], v[84:87], v[2:17]
	v_cmp_nlt_f32_e32 vcc, s27, v71
	v_cmp_ngt_f32_e64 s[0:1], s26, v71
	s_or_b64 s[2:3], vcc, s[0:1]
	v_mfma_f32_32x32x16_bf16 v[2:17], v[72:75], v[88:91], v[2:17]
	v_mfma_f32_32x32x16_bf16 v[2:17], v[76:79], v[92:95], v[2:17]
	v_mfma_f32_32x32x16_bf16 v[2:17], v[80:83], v[96:99], v[2:17]
	s_and_saveexec_b64 s[0:1], s[2:3]
	s_cbranch_execz .LBB0_482
	s_mov_b64 s[2:3], src_shared_base
	s_add_i32 s2, 0, 0x1d000
	s_cmp_lg_u32 s2, -1
	s_cselect_b32 s2, s2, 0
	s_cselect_b32 s3, s3, 0
	v_mov_b32_e32 v66, s2
	v_mov_b32_e32 v67, s3
	flat_store_dword v[66:67], v175 sc0 sc1
	s_waitcnt vmcnt(0)
